# also: transpose/row-pass d loads batched, filter-synthesis loop LDS weight reads issued one block ahead
# speedup vs baseline: 1.0604x; 1.0088x over previous
; __device__ void transpose_hy(const Params& p, unsigned char* shm) {
;     ...
;   for (int t = blockIdx.x; t < ntile; t += gridDim.x) {
;     const int ct = t & 15, tt = t >> 4, tok0 = tt * 64;
;     const bf16_t* src; int L;
;     if (tok0 < MP) { L = LP; src = hyT + (size_t)(tok0 >> 14) * 3072 * LP + (tok0 & (LP - 1)); }
;     else { L = LSQ; const int tk = tok0 - MP; src = hyT + (size_t)2 * 3072 * LP + (size_t)(tk >> 13) * 3072 * LSQ + (tk & (LSQ - 1)); }
;     __syncthreads();
; #pragma unroll
;     for (int i = 0; i < 4; ++i) { const int e = tid + i * 512, cr = e >> 5, tp = (e & 31) * 2; *(unsigned*)(tile + cr * 66 + tp) = *(const unsigned*)(src + (size_t)(ct * 64 + cr) * L + tp); }
.LBB0_423:
	s_and_b32 s1, s1, s5
	s_lshl_b32 s1, s1, 1
	s_add_u32 s14, s14, s1
	s_addc_u32 s15, s15, 0
	s_and_b32 s20, s7, 0x3c0
	v_add_u32_e32 v16, s20, v2
	v_lshl_add_u64 v[14:15], s[14:15], 0, v[32:33]
	v_mad_i64_i32 v[16:17], s[14:15], s0, v16, 0
	v_lshl_add_u64 v[16:17], v[16:17], 1, v[14:15]
	s_waitcnt vmcnt(0) lgkmcnt(0)
	s_barrier
	global_load_dword v230, v[16:17], off
	s_add_i32 s7, s7, s57


; __device__ void transpose_hy(const Params& p, unsigned char* shm) {
;     ...
;     for (int i = 0; i < 4; ++i) { const int e = tid + i * 512, cr = e >> 5, tp = (e & 31) * 2; *(unsigned*)(tile + cr * 66 + tp) = *(const unsigned*)(src + (size_t)(ct * 64 + cr) * L + tp); }
	v_add_u32_e32 v16, s20, v4
	v_mad_i64_i32 v[16:17], s[14:15], s0, v16, 0
	v_lshl_add_u64 v[16:17], v[16:17], 1, v[14:15]
	global_load_dword v231, v[16:17], off


; __device__ void transpose_hy(const Params& p, unsigned char* shm) {
;     ...
;     for (int i = 0; i < 4; ++i) { const int e = tid + i * 512, cr = e >> 5, tp = (e & 31) * 2; *(unsigned*)(tile + cr * 66 + tp) = *(const unsigned*)(src + (size_t)(ct * 64 + cr) * L + tp); }
	v_add_u32_e32 v16, s20, v5
	v_mad_i64_i32 v[16:17], s[14:15], s0, v16, 0
	v_lshl_add_u64 v[16:17], v[16:17], 1, v[14:15]
	global_load_dword v232, v[16:17], off


; __device__ void transpose_hy(const Params& p, unsigned char* shm) {
;     ...
;     for (int i = 0; i < 4; ++i) { const int e = tid + i * 512, cr = e >> 5, tp = (e & 31) * 2; *(unsigned*)(tile + cr * 66 + tp) = *(const unsigned*)(src + (size_t)(ct * 64 + cr) * L + tp); }
	v_add_u32_e32 v16, s20, v6
	v_mad_i64_i32 v[16:17], s[0:1], s0, v16, 0
	v_lshl_add_u64 v[14:15], v[16:17], 1, v[14:15]
	global_load_dword v233, v[14:15], off
	s_waitcnt vmcnt(0)
	ds_write_b32 v10, v230
	ds_write_b32 v11, v231
	ds_write_b32 v12, v232
	ds_write_b32 v13, v233
	s_lshl_b32 s0, s20, 1
	s_mov_b32 s1, s94


; __device__ void transpose_hy(const Params& p, unsigned char* shm) {
;     ...
;     __syncthreads();
; #pragma unroll
;     for (int i = 0; i < 4; ++i) { const int e = tid + i * 512, tr = e >> 5, cp = (e & 31) * 2;
;       const unsigned w = (unsigned)tile[cp * 66 + tr] | ((unsigned)tile[(cp + 1) * 66 + tr] << 16);
;       *(unsigned*)(hy + (size_t)(tok0 + tr) * DHY + ct * 64 + cp) = w; }
	s_waitcnt lgkmcnt(0)
	s_barrier
	ds_read_u16 v16, v3
	ds_read_u16 v17, v3 offset:132
	v_lshl_add_u64 v[14:15], v[0:1], 0, s[0:1]
	v_readlane_b32 s0, v251, 12
	s_add_i32 s11, s11, s0
	v_readlane_b32 s0, v253, 20
	s_waitcnt lgkmcnt(0)
	v_lshl_or_b32 v18, v17, 16, v16
	v_add_u32_e32 v16, s17, v2
	v_ashrrev_i32_e32 v17, 31, v16
	v_lshlrev_b64 v[16:17], 11, v[16:17]
	v_lshl_add_u64 v[16:17], v[14:15], 0, v[16:17]
	global_store_dword v[16:17], v18, off
	ds_read_u16 v16, v7
	ds_read_u16 v17, v7 offset:132
	s_add_i32 s5, s5, s0
	s_cmpk_lt_i32 s11, 0x3000
	v_readlane_b32 s1, v251, 13
	s_waitcnt lgkmcnt(0)
	v_lshl_or_b32 v18, v17, 16, v16
	v_add_u32_e32 v16, s17, v4
	v_ashrrev_i32_e32 v17, 31, v16
	v_lshlrev_b64 v[16:17], 11, v[16:17]
	v_lshl_add_u64 v[16:17], v[14:15], 0, v[16:17]
	global_store_dword v[16:17], v18, off
	ds_read_u16 v16, v8
	ds_read_u16 v17, v8 offset:132
	s_waitcnt lgkmcnt(0)
	v_lshl_or_b32 v18, v17, 16, v16
	v_add_u32_e32 v16, s17, v5
	v_ashrrev_i32_e32 v17, 31, v16
	v_lshlrev_b64 v[16:17], 11, v[16:17]
	v_lshl_add_u64 v[16:17], v[14:15], 0, v[16:17]
	global_store_dword v[16:17], v18, off
	ds_read_u16 v16, v9
	ds_read_u16 v17, v9 offset:132
	s_waitcnt lgkmcnt(0)
	v_lshl_or_b32 v18, v17, 16, v16
	v_add_u32_e32 v16, s17, v6
	v_ashrrev_i32_e32 v17, 31, v16
	v_lshlrev_b64 v[16:17], 11, v[16:17]
	v_lshl_add_u64 v[14:15], v[14:15], 0, v[16:17]
	global_store_dword v[14:15], v18, off
	s_cbranch_scc0 .LBB0_428

; template <int LOGN>
; __device__ void hyena_filters(const Params& p, unsigned char* shm, int c0, int cstride) {
;     ...
;     for (int j0 = 0; j0 < 64; j0 += 8) {
;       f32x4 hv[8];
; #pragma unroll
;       for (int j = 0; j < 8; ++j) hv[j] = *(const f32x4*)(h3T + (size_t)(j0 + j) * L + t4);
; #pragma unroll
;       for (int j = 0; j < 8; ++j) {
;         const f32x4* wp = (const f32x4*)(sW + (j0 + j) * 16);
; #pragma unroll
;         for (int q = 0; q < 4; ++q) { const f32x4 w = wp[q]; acc[q * 4] += hv[j] * w[0]; acc[q * 4 + 1] += hv[j] * w[1]; acc[q * 4 + 2] += hv[j] * w[2]; acc[q * 4 + 3] += hv[j] * w[3]; }
;       }
.LBB0_510:
	s_mov_b32 s11, 0xfff90000
	v_add_co_u32_e32 v0, vcc, s11, v34
	s_mov_b32 s11, 0xfffa0000
	s_nop 0
	v_addc_co_u32_e32 v1, vcc, -1, v35, vcc
	global_load_dwordx4 v[88:91], v[0:1], off
	v_add_co_u32_e32 v0, vcc, s11, v34
	s_mov_b32 s11, 0xfffb0000
	s_nop 0
	v_addc_co_u32_e32 v1, vcc, -1, v35, vcc
	global_load_dwordx4 v[92:95], v[0:1], off
	v_add_co_u32_e32 v0, vcc, s11, v34
	s_mov_b32 s11, 0xfffc0000
	s_nop 0
	v_addc_co_u32_e32 v1, vcc, -1, v35, vcc
	global_load_dwordx4 v[96:99], v[0:1], off
	v_add_co_u32_e32 v0, vcc, s11, v34
	v_mov_b32_e32 v13, s5
	s_nop 0
	v_addc_co_u32_e32 v1, vcc, -1, v35, vcc
	global_load_dwordx4 v[100:103], v[0:1], off
	v_add_co_u32_e32 v0, vcc, s24, v34
	s_add_i32 s7, s7, 8
	s_nop 0
	v_addc_co_u32_e32 v1, vcc, -1, v35, vcc
	global_load_dwordx4 v[104:107], v[0:1], off
	v_add_co_u32_e32 v0, vcc, s25, v34
	s_addk_i32 s5, 0x200
	s_nop 0
	v_addc_co_u32_e32 v1, vcc, -1, v35, vcc
	global_load_dwordx4 v[8:11], v[0:1], off
	v_add_co_u32_e32 v0, vcc, s66, v34
	s_cmp_gt_u32 s7, 55
	s_nop 0
	v_addc_co_u32_e32 v1, vcc, -1, v35, vcc
	global_load_dwordx4 v[4:7], v[0:1], off
	s_nop 0
	global_load_dwordx4 v[0:3], v[34:35], off
	ds_read_b128 v[108:111], v13
	ds_read_b128 v[112:115], v13 offset:16
	ds_read_b128 v[116:119], v13 offset:32
	ds_read_b128 v[120:123], v13 offset:48
	v_lshl_add_u64 v[34:35], v[34:35], 0, s[14:15]
	s_waitcnt vmcnt(7) lgkmcnt(3)
	v_pk_fma_f32 v[82:83], v[90:91], v[108:109], v[82:83] op_sel_hi:[1,0,1]
	v_pk_fma_f32 v[80:81], v[88:89], v[108:109], v[80:81] op_sel_hi:[1,0,1]
	v_pk_fma_f32 v[78:79], v[90:91], v[108:109], v[78:79] op_sel:[0,1,0]
	v_pk_fma_f32 v[76:77], v[88:89], v[108:109], v[76:77] op_sel:[0,1,0]
	v_mov_b32_e32 v108, v111
	v_pk_fma_f32 v[70:71], v[90:91], v[108:109], v[70:71] op_sel_hi:[1,0,1]
	v_pk_fma_f32 v[68:69], v[88:89], v[108:109], v[68:69] op_sel_hi:[1,0,1]
	s_waitcnt lgkmcnt(2)
	v_mov_b32_e32 v108, v115
	v_pk_fma_f32 v[54:55], v[90:91], v[108:109], v[54:55] op_sel_hi:[1,0,1]
	v_pk_fma_f32 v[48:49], v[88:89], v[108:109], v[48:49] op_sel_hi:[1,0,1]
	s_waitcnt lgkmcnt(1)
	v_mov_b32_e32 v108, v119
	v_pk_fma_f32 v[38:39], v[90:91], v[108:109], v[38:39] op_sel_hi:[1,0,1]
	v_pk_fma_f32 v[36:37], v[88:89], v[108:109], v[36:37] op_sel_hi:[1,0,1]
	s_waitcnt lgkmcnt(0)
	v_mov_b32_e32 v108, v123
	v_pk_fma_f32 v[74:75], v[90:91], v[110:111], v[74:75] op_sel_hi:[1,0,1]
	v_pk_fma_f32 v[72:73], v[88:89], v[110:111], v[72:73] op_sel_hi:[1,0,1]
	v_pk_fma_f32 v[66:67], v[90:91], v[112:113], v[66:67] op_sel_hi:[1,0,1]
	v_pk_fma_f32 v[64:65], v[88:89], v[112:113], v[64:65] op_sel_hi:[1,0,1]
	v_pk_fma_f32 v[62:63], v[90:91], v[112:113], v[62:63] op_sel:[0,1,0]
	v_pk_fma_f32 v[60:61], v[88:89], v[112:113], v[60:61] op_sel:[0,1,0]
	v_pk_fma_f32 v[58:59], v[90:91], v[114:115], v[58:59] op_sel_hi:[1,0,1]
	v_pk_fma_f32 v[56:57], v[88:89], v[114:115], v[56:57] op_sel_hi:[1,0,1]
	v_pk_fma_f32 v[52:53], v[90:91], v[116:117], v[52:53] op_sel_hi:[1,0,1]
	v_pk_fma_f32 v[50:51], v[88:89], v[116:117], v[50:51] op_sel_hi:[1,0,1]
	v_pk_fma_f32 v[46:47], v[90:91], v[116:117], v[46:47] op_sel:[0,1,0]
	v_pk_fma_f32 v[44:45], v[88:89], v[116:117], v[44:45] op_sel:[0,1,0]
	v_pk_fma_f32 v[42:43], v[90:91], v[118:119], v[42:43] op_sel_hi:[1,0,1]
	v_pk_fma_f32 v[40:41], v[88:89], v[118:119], v[40:41] op_sel_hi:[1,0,1]
	v_pk_fma_f32 v[30:31], v[90:91], v[120:121], v[30:31] op_sel_hi:[1,0,1]
	v_pk_fma_f32 v[28:29], v[88:89], v[120:121], v[28:29] op_sel_hi:[1,0,1]
	v_pk_fma_f32 v[26:27], v[90:91], v[120:121], v[26:27] op_sel:[0,1,0]
	v_pk_fma_f32 v[24:25], v[88:89], v[120:121], v[24:25] op_sel:[0,1,0]
	v_pk_fma_f32 v[22:23], v[90:91], v[122:123], v[22:23] op_sel_hi:[1,0,1]
	v_pk_fma_f32 v[20:21], v[88:89], v[122:123], v[20:21] op_sel_hi:[1,0,1]
	v_pk_fma_f32 v[90:91], v[90:91], v[108:109], v[18:19] op_sel_hi:[1,0,1]
	v_pk_fma_f32 v[88:89], v[88:89], v[108:109], v[16:17] op_sel_hi:[1,0,1]
	ds_read_b128 v[208:211], v13 offset:64
	ds_read_b128 v[212:215], v13 offset:80
	s_waitcnt vmcnt(6) lgkmcnt(1)
	v_pk_fma_f32 v[82:83], v[94:95], v[208:209], v[82:83] op_sel_hi:[1,0,1]
	v_pk_fma_f32 v[80:81], v[92:93], v[208:209], v[80:81] op_sel_hi:[1,0,1]
	v_pk_fma_f32 v[78:79], v[94:95], v[208:209], v[78:79] op_sel:[0,1,0]
	v_pk_fma_f32 v[76:77], v[92:93], v[208:209], v[76:77] op_sel:[0,1,0]
	v_mov_b32_e32 v208, v211
	v_pk_fma_f32 v[74:75], v[94:95], v[210:211], v[74:75] op_sel_hi:[1,0,1]
	v_pk_fma_f32 v[72:73], v[92:93], v[210:211], v[72:73] op_sel_hi:[1,0,1]
	v_pk_fma_f32 v[70:71], v[94:95], v[208:209], v[70:71] op_sel_hi:[1,0,1]
	v_pk_fma_f32 v[68:69], v[92:93], v[208:209], v[68:69] op_sel_hi:[1,0,1]
	ds_read_b128 v[208:211], v13 offset:96
	s_waitcnt lgkmcnt(1)
	v_pk_fma_f32 v[66:67], v[94:95], v[212:213], v[66:67] op_sel_hi:[1,0,1]
	v_pk_fma_f32 v[64:65], v[92:93], v[212:213], v[64:65] op_sel_hi:[1,0,1]
	v_pk_fma_f32 v[62:63], v[94:95], v[212:213], v[62:63] op_sel:[0,1,0]
	v_pk_fma_f32 v[60:61], v[92:93], v[212:213], v[60:61] op_sel:[0,1,0]
	v_mov_b32_e32 v212, v215
	v_pk_fma_f32 v[58:59], v[94:95], v[214:215], v[58:59] op_sel_hi:[1,0,1]
	v_pk_fma_f32 v[56:57], v[92:93], v[214:215], v[56:57] op_sel_hi:[1,0,1]
	v_pk_fma_f32 v[54:55], v[94:95], v[212:213], v[54:55] op_sel_hi:[1,0,1]
	v_pk_fma_f32 v[48:49], v[92:93], v[212:213], v[48:49] op_sel_hi:[1,0,1]
	ds_read_b128 v[212:215], v13 offset:112
	s_waitcnt lgkmcnt(1)
; template <int LOGN>
; __device__ void hyena_filters(const Params& p, unsigned char* shm, int c0, int cstride) {
;     ...
;       for (int j = 0; j < 8; ++j) {
;         const f32x4* wp = (const f32x4*)(sW + (j0 + j) * 16);
; #pragma unroll
;         for (int q = 0; q < 4; ++q) { const f32x4 w = wp[q]; acc[q * 4] += hv[j] * w[0]; acc[q * 4 + 1] += hv[j] * w[1]; acc[q * 4 + 2] += hv[j] * w[2]; acc[q * 4 + 3] += hv[j] * w[3]; }
;       }
	v_pk_fma_f32 v[52:53], v[94:95], v[208:209], v[52:53] op_sel_hi:[1,0,1]
	v_pk_fma_f32 v[50:51], v[92:93], v[208:209], v[50:51] op_sel_hi:[1,0,1]
	v_pk_fma_f32 v[46:47], v[94:95], v[208:209], v[46:47] op_sel:[0,1,0]
	v_pk_fma_f32 v[44:45], v[92:93], v[208:209], v[44:45] op_sel:[0,1,0]
	v_mov_b32_e32 v208, v211
	v_pk_fma_f32 v[42:43], v[94:95], v[210:211], v[42:43] op_sel_hi:[1,0,1]
	v_pk_fma_f32 v[40:41], v[92:93], v[210:211], v[40:41] op_sel_hi:[1,0,1]
	v_pk_fma_f32 v[38:39], v[94:95], v[208:209], v[38:39] op_sel_hi:[1,0,1]
	v_pk_fma_f32 v[36:37], v[92:93], v[208:209], v[36:37] op_sel_hi:[1,0,1]
	ds_read_b128 v[208:211], v13 offset:128
	s_waitcnt lgkmcnt(1)
	v_pk_fma_f32 v[30:31], v[94:95], v[212:213], v[30:31] op_sel_hi:[1,0,1]
	v_pk_fma_f32 v[28:29], v[92:93], v[212:213], v[28:29] op_sel_hi:[1,0,1]
	v_pk_fma_f32 v[26:27], v[94:95], v[212:213], v[26:27] op_sel:[0,1,0]
	v_pk_fma_f32 v[24:25], v[92:93], v[212:213], v[24:25] op_sel:[0,1,0]
	v_mov_b32_e32 v212, v215
	v_pk_fma_f32 v[22:23], v[94:95], v[214:215], v[22:23] op_sel_hi:[1,0,1]
	v_pk_fma_f32 v[20:21], v[92:93], v[214:215], v[20:21] op_sel_hi:[1,0,1]
	v_pk_fma_f32 v[90:91], v[94:95], v[212:213], v[90:91] op_sel_hi:[1,0,1]
	v_pk_fma_f32 v[88:89], v[92:93], v[212:213], v[88:89] op_sel_hi:[1,0,1]
	ds_read_b128 v[212:215], v13 offset:144
	s_waitcnt vmcnt(5) lgkmcnt(1)
	v_pk_fma_f32 v[82:83], v[98:99], v[208:209], v[82:83] op_sel_hi:[1,0,1]
	v_pk_fma_f32 v[80:81], v[96:97], v[208:209], v[80:81] op_sel_hi:[1,0,1]
	v_pk_fma_f32 v[78:79], v[98:99], v[208:209], v[78:79] op_sel:[0,1,0]
	v_pk_fma_f32 v[76:77], v[96:97], v[208:209], v[76:77] op_sel:[0,1,0]
	v_mov_b32_e32 v208, v211
	v_pk_fma_f32 v[74:75], v[98:99], v[210:211], v[74:75] op_sel_hi:[1,0,1]
	v_pk_fma_f32 v[72:73], v[96:97], v[210:211], v[72:73] op_sel_hi:[1,0,1]
	v_pk_fma_f32 v[70:71], v[98:99], v[208:209], v[70:71] op_sel_hi:[1,0,1]
	v_pk_fma_f32 v[68:69], v[96:97], v[208:209], v[68:69] op_sel_hi:[1,0,1]
	ds_read_b128 v[208:211], v13 offset:160
	s_waitcnt lgkmcnt(1)
	v_pk_fma_f32 v[66:67], v[98:99], v[212:213], v[66:67] op_sel_hi:[1,0,1]
	v_pk_fma_f32 v[64:65], v[96:97], v[212:213], v[64:65] op_sel_hi:[1,0,1]
	v_pk_fma_f32 v[62:63], v[98:99], v[212:213], v[62:63] op_sel:[0,1,0]
	v_pk_fma_f32 v[60:61], v[96:97], v[212:213], v[60:61] op_sel:[0,1,0]
	v_mov_b32_e32 v212, v215
	v_pk_fma_f32 v[58:59], v[98:99], v[214:215], v[58:59] op_sel_hi:[1,0,1]
	v_pk_fma_f32 v[56:57], v[96:97], v[214:215], v[56:57] op_sel_hi:[1,0,1]
	v_pk_fma_f32 v[54:55], v[98:99], v[212:213], v[54:55] op_sel_hi:[1,0,1]
	v_pk_fma_f32 v[48:49], v[96:97], v[212:213], v[48:49] op_sel_hi:[1,0,1]
	ds_read_b128 v[212:215], v13 offset:176
	s_waitcnt lgkmcnt(1)
	v_pk_fma_f32 v[52:53], v[98:99], v[208:209], v[52:53] op_sel_hi:[1,0,1]
	v_pk_fma_f32 v[50:51], v[96:97], v[208:209], v[50:51] op_sel_hi:[1,0,1]
	v_pk_fma_f32 v[46:47], v[98:99], v[208:209], v[46:47] op_sel:[0,1,0]
	v_pk_fma_f32 v[44:45], v[96:97], v[208:209], v[44:45] op_sel:[0,1,0]
	v_mov_b32_e32 v208, v211
	v_pk_fma_f32 v[42:43], v[98:99], v[210:211], v[42:43] op_sel_hi:[1,0,1]
	v_pk_fma_f32 v[40:41], v[96:97], v[210:211], v[40:41] op_sel_hi:[1,0,1]
	v_pk_fma_f32 v[38:39], v[98:99], v[208:209], v[38:39] op_sel_hi:[1,0,1]
	v_pk_fma_f32 v[36:37], v[96:97], v[208:209], v[36:37] op_sel_hi:[1,0,1]
	ds_read_b128 v[208:211], v13 offset:192
	s_waitcnt lgkmcnt(1)
	v_pk_fma_f32 v[30:31], v[98:99], v[212:213], v[30:31] op_sel_hi:[1,0,1]
	v_pk_fma_f32 v[28:29], v[96:97], v[212:213], v[28:29] op_sel_hi:[1,0,1]
	v_pk_fma_f32 v[26:27], v[98:99], v[212:213], v[26:27] op_sel:[0,1,0]
	v_pk_fma_f32 v[24:25], v[96:97], v[212:213], v[24:25] op_sel:[0,1,0]
	v_mov_b32_e32 v212, v215
	v_pk_fma_f32 v[22:23], v[98:99], v[214:215], v[22:23] op_sel_hi:[1,0,1]
	v_pk_fma_f32 v[20:21], v[96:97], v[214:215], v[20:21] op_sel_hi:[1,0,1]
	v_pk_fma_f32 v[90:91], v[98:99], v[212:213], v[90:91] op_sel_hi:[1,0,1]
	v_pk_fma_f32 v[88:89], v[96:97], v[212:213], v[88:89] op_sel_hi:[1,0,1]
	ds_read_b128 v[212:215], v13 offset:208
	s_waitcnt vmcnt(4) lgkmcnt(1)
	v_pk_fma_f32 v[82:83], v[102:103], v[208:209], v[82:83] op_sel_hi:[1,0,1]
	v_pk_fma_f32 v[80:81], v[100:101], v[208:209], v[80:81] op_sel_hi:[1,0,1]
	v_pk_fma_f32 v[78:79], v[102:103], v[208:209], v[78:79] op_sel:[0,1,0]
	v_pk_fma_f32 v[76:77], v[100:101], v[208:209], v[76:77] op_sel:[0,1,0]
	v_mov_b32_e32 v208, v211
	v_pk_fma_f32 v[74:75], v[102:103], v[210:211], v[74:75] op_sel_hi:[1,0,1]
	v_pk_fma_f32 v[72:73], v[100:101], v[210:211], v[72:73] op_sel_hi:[1,0,1]
	v_pk_fma_f32 v[70:71], v[102:103], v[208:209], v[70:71] op_sel_hi:[1,0,1]
	v_pk_fma_f32 v[68:69], v[100:101], v[208:209], v[68:69] op_sel_hi:[1,0,1]
	ds_read_b128 v[208:211], v13 offset:224
	s_waitcnt lgkmcnt(1)
	v_pk_fma_f32 v[66:67], v[102:103], v[212:213], v[66:67] op_sel_hi:[1,0,1]
	v_pk_fma_f32 v[64:65], v[100:101], v[212:213], v[64:65] op_sel_hi:[1,0,1]
	v_pk_fma_f32 v[62:63], v[102:103], v[212:213], v[62:63] op_sel:[0,1,0]
	v_pk_fma_f32 v[60:61], v[100:101], v[212:213], v[60:61] op_sel:[0,1,0]
	v_mov_b32_e32 v212, v215
	v_pk_fma_f32 v[58:59], v[102:103], v[214:215], v[58:59] op_sel_hi:[1,0,1]
	v_pk_fma_f32 v[56:57], v[100:101], v[214:215], v[56:57] op_sel_hi:[1,0,1]
	v_pk_fma_f32 v[54:55], v[102:103], v[212:213], v[54:55] op_sel_hi:[1,0,1]
	v_pk_fma_f32 v[48:49], v[100:101], v[212:213], v[48:49] op_sel_hi:[1,0,1]
	ds_read_b128 v[212:215], v13 offset:240
	s_waitcnt lgkmcnt(1)
; template <int LOGN>
; __device__ void hyena_filters(const Params& p, unsigned char* shm, int c0, int cstride) {
;     ...
;       for (int j = 0; j < 8; ++j) {
;         const f32x4* wp = (const f32x4*)(sW + (j0 + j) * 16);
; #pragma unroll
;         for (int q = 0; q < 4; ++q) { const f32x4 w = wp[q]; acc[q * 4] += hv[j] * w[0]; acc[q * 4 + 1] += hv[j] * w[1]; acc[q * 4 + 2] += hv[j] * w[2]; acc[q * 4 + 3] += hv[j] * w[3]; }
;       }
	v_pk_fma_f32 v[52:53], v[102:103], v[208:209], v[52:53] op_sel_hi:[1,0,1]
	v_pk_fma_f32 v[50:51], v[100:101], v[208:209], v[50:51] op_sel_hi:[1,0,1]
	v_pk_fma_f32 v[46:47], v[102:103], v[208:209], v[46:47] op_sel:[0,1,0]
	v_pk_fma_f32 v[44:45], v[100:101], v[208:209], v[44:45] op_sel:[0,1,0]
	v_mov_b32_e32 v208, v211
	v_pk_fma_f32 v[42:43], v[102:103], v[210:211], v[42:43] op_sel_hi:[1,0,1]
	v_pk_fma_f32 v[40:41], v[100:101], v[210:211], v[40:41] op_sel_hi:[1,0,1]
	v_pk_fma_f32 v[38:39], v[102:103], v[208:209], v[38:39] op_sel_hi:[1,0,1]
	v_pk_fma_f32 v[36:37], v[100:101], v[208:209], v[36:37] op_sel_hi:[1,0,1]
	ds_read_b128 v[208:211], v13 offset:256
	s_waitcnt lgkmcnt(1)
	v_pk_fma_f32 v[30:31], v[102:103], v[212:213], v[30:31] op_sel_hi:[1,0,1]
	v_pk_fma_f32 v[28:29], v[100:101], v[212:213], v[28:29] op_sel_hi:[1,0,1]
	v_pk_fma_f32 v[26:27], v[102:103], v[212:213], v[26:27] op_sel:[0,1,0]
	v_pk_fma_f32 v[24:25], v[100:101], v[212:213], v[24:25] op_sel:[0,1,0]
	v_mov_b32_e32 v212, v215
	v_pk_fma_f32 v[22:23], v[102:103], v[214:215], v[22:23] op_sel_hi:[1,0,1]
	v_pk_fma_f32 v[20:21], v[100:101], v[214:215], v[20:21] op_sel_hi:[1,0,1]
	v_pk_fma_f32 v[90:91], v[102:103], v[212:213], v[90:91] op_sel_hi:[1,0,1]
	v_pk_fma_f32 v[88:89], v[100:101], v[212:213], v[88:89] op_sel_hi:[1,0,1]
	ds_read_b128 v[212:215], v13 offset:272
	s_waitcnt vmcnt(3) lgkmcnt(1)
	v_pk_fma_f32 v[82:83], v[106:107], v[208:209], v[82:83] op_sel_hi:[1,0,1]
	v_pk_fma_f32 v[80:81], v[104:105], v[208:209], v[80:81] op_sel_hi:[1,0,1]
	v_pk_fma_f32 v[78:79], v[106:107], v[208:209], v[78:79] op_sel:[0,1,0]
	v_pk_fma_f32 v[76:77], v[104:105], v[208:209], v[76:77] op_sel:[0,1,0]
	v_mov_b32_e32 v208, v211
	v_pk_fma_f32 v[74:75], v[106:107], v[210:211], v[74:75] op_sel_hi:[1,0,1]
	v_pk_fma_f32 v[72:73], v[104:105], v[210:211], v[72:73] op_sel_hi:[1,0,1]
	v_pk_fma_f32 v[70:71], v[106:107], v[208:209], v[70:71] op_sel_hi:[1,0,1]
	v_pk_fma_f32 v[68:69], v[104:105], v[208:209], v[68:69] op_sel_hi:[1,0,1]
	ds_read_b128 v[208:211], v13 offset:288
	s_waitcnt lgkmcnt(1)
	v_pk_fma_f32 v[66:67], v[106:107], v[212:213], v[66:67] op_sel_hi:[1,0,1]
	v_pk_fma_f32 v[64:65], v[104:105], v[212:213], v[64:65] op_sel_hi:[1,0,1]
	v_pk_fma_f32 v[62:63], v[106:107], v[212:213], v[62:63] op_sel:[0,1,0]
	v_pk_fma_f32 v[60:61], v[104:105], v[212:213], v[60:61] op_sel:[0,1,0]
	v_mov_b32_e32 v212, v215
	v_pk_fma_f32 v[58:59], v[106:107], v[214:215], v[58:59] op_sel_hi:[1,0,1]
	v_pk_fma_f32 v[56:57], v[104:105], v[214:215], v[56:57] op_sel_hi:[1,0,1]
	v_pk_fma_f32 v[54:55], v[106:107], v[212:213], v[54:55] op_sel_hi:[1,0,1]
	v_pk_fma_f32 v[48:49], v[104:105], v[212:213], v[48:49] op_sel_hi:[1,0,1]
	ds_read_b128 v[212:215], v13 offset:304
	s_waitcnt lgkmcnt(1)
	v_pk_fma_f32 v[52:53], v[106:107], v[208:209], v[52:53] op_sel_hi:[1,0,1]
	v_pk_fma_f32 v[50:51], v[104:105], v[208:209], v[50:51] op_sel_hi:[1,0,1]
	v_pk_fma_f32 v[46:47], v[106:107], v[208:209], v[46:47] op_sel:[0,1,0]
	v_pk_fma_f32 v[44:45], v[104:105], v[208:209], v[44:45] op_sel:[0,1,0]
	v_mov_b32_e32 v208, v211
	v_pk_fma_f32 v[42:43], v[106:107], v[210:211], v[42:43] op_sel_hi:[1,0,1]
	v_pk_fma_f32 v[40:41], v[104:105], v[210:211], v[40:41] op_sel_hi:[1,0,1]
	v_pk_fma_f32 v[38:39], v[106:107], v[208:209], v[38:39] op_sel_hi:[1,0,1]
	v_pk_fma_f32 v[36:37], v[104:105], v[208:209], v[36:37] op_sel_hi:[1,0,1]
	ds_read_b128 v[208:211], v13 offset:320
	s_waitcnt lgkmcnt(1)
	v_pk_fma_f32 v[30:31], v[106:107], v[212:213], v[30:31] op_sel_hi:[1,0,1]
	v_pk_fma_f32 v[28:29], v[104:105], v[212:213], v[28:29] op_sel_hi:[1,0,1]
	v_pk_fma_f32 v[26:27], v[106:107], v[212:213], v[26:27] op_sel:[0,1,0]
	v_pk_fma_f32 v[24:25], v[104:105], v[212:213], v[24:25] op_sel:[0,1,0]
	v_mov_b32_e32 v212, v215
	v_pk_fma_f32 v[22:23], v[106:107], v[214:215], v[22:23] op_sel_hi:[1,0,1]
	v_pk_fma_f32 v[20:21], v[104:105], v[214:215], v[20:21] op_sel_hi:[1,0,1]
	v_pk_fma_f32 v[90:91], v[106:107], v[212:213], v[90:91] op_sel_hi:[1,0,1]
	v_pk_fma_f32 v[88:89], v[104:105], v[212:213], v[88:89] op_sel_hi:[1,0,1]
	ds_read_b128 v[212:215], v13 offset:336
	s_waitcnt vmcnt(2) lgkmcnt(1)
	v_pk_fma_f32 v[82:83], v[10:11], v[208:209], v[82:83] op_sel_hi:[1,0,1]
	v_pk_fma_f32 v[80:81], v[8:9], v[208:209], v[80:81] op_sel_hi:[1,0,1]
	v_pk_fma_f32 v[78:79], v[10:11], v[208:209], v[78:79] op_sel:[0,1,0]
	v_pk_fma_f32 v[76:77], v[8:9], v[208:209], v[76:77] op_sel:[0,1,0]
	v_mov_b32_e32 v208, v211
	v_pk_fma_f32 v[74:75], v[10:11], v[210:211], v[74:75] op_sel_hi:[1,0,1]
	v_pk_fma_f32 v[72:73], v[8:9], v[210:211], v[72:73] op_sel_hi:[1,0,1]
	v_pk_fma_f32 v[70:71], v[10:11], v[208:209], v[70:71] op_sel_hi:[1,0,1]
	v_pk_fma_f32 v[68:69], v[8:9], v[208:209], v[68:69] op_sel_hi:[1,0,1]
	ds_read_b128 v[208:211], v13 offset:352
	s_waitcnt lgkmcnt(1)
	v_pk_fma_f32 v[66:67], v[10:11], v[212:213], v[66:67] op_sel_hi:[1,0,1]
	v_pk_fma_f32 v[64:65], v[8:9], v[212:213], v[64:65] op_sel_hi:[1,0,1]
	v_pk_fma_f32 v[62:63], v[10:11], v[212:213], v[62:63] op_sel:[0,1,0]
	v_pk_fma_f32 v[60:61], v[8:9], v[212:213], v[60:61] op_sel:[0,1,0]
	v_mov_b32_e32 v212, v215
	v_pk_fma_f32 v[58:59], v[10:11], v[214:215], v[58:59] op_sel_hi:[1,0,1]
	v_pk_fma_f32 v[56:57], v[8:9], v[214:215], v[56:57] op_sel_hi:[1,0,1]
	v_pk_fma_f32 v[54:55], v[10:11], v[212:213], v[54:55] op_sel_hi:[1,0,1]
	v_pk_fma_f32 v[48:49], v[8:9], v[212:213], v[48:49] op_sel_hi:[1,0,1]
	ds_read_b128 v[212:215], v13 offset:368
	s_waitcnt lgkmcnt(1)
; template <int LOGN>
; __device__ void hyena_filters(const Params& p, unsigned char* shm, int c0, int cstride) {
;     ...
;       for (int j = 0; j < 8; ++j) {
;         const f32x4* wp = (const f32x4*)(sW + (j0 + j) * 16);
; #pragma unroll
;         for (int q = 0; q < 4; ++q) { const f32x4 w = wp[q]; acc[q * 4] += hv[j] * w[0]; acc[q * 4 + 1] += hv[j] * w[1]; acc[q * 4 + 2] += hv[j] * w[2]; acc[q * 4 + 3] += hv[j] * w[3]; }
;       }
	v_pk_fma_f32 v[52:53], v[10:11], v[208:209], v[52:53] op_sel_hi:[1,0,1]
	v_pk_fma_f32 v[50:51], v[8:9], v[208:209], v[50:51] op_sel_hi:[1,0,1]
	v_pk_fma_f32 v[46:47], v[10:11], v[208:209], v[46:47] op_sel:[0,1,0]
	v_pk_fma_f32 v[44:45], v[8:9], v[208:209], v[44:45] op_sel:[0,1,0]
	v_mov_b32_e32 v208, v211
	v_pk_fma_f32 v[42:43], v[10:11], v[210:211], v[42:43] op_sel_hi:[1,0,1]
	v_pk_fma_f32 v[40:41], v[8:9], v[210:211], v[40:41] op_sel_hi:[1,0,1]
	v_pk_fma_f32 v[38:39], v[10:11], v[208:209], v[38:39] op_sel_hi:[1,0,1]
	v_pk_fma_f32 v[36:37], v[8:9], v[208:209], v[36:37] op_sel_hi:[1,0,1]
	ds_read_b128 v[208:211], v13 offset:384
	s_waitcnt lgkmcnt(1)
	v_pk_fma_f32 v[22:23], v[10:11], v[214:215], v[22:23] op_sel_hi:[1,0,1]
	v_pk_fma_f32 v[20:21], v[8:9], v[214:215], v[20:21] op_sel_hi:[1,0,1]
	v_mov_b32_e32 v214, v215
	v_pk_fma_f32 v[30:31], v[10:11], v[212:213], v[30:31] op_sel_hi:[1,0,1]
	v_pk_fma_f32 v[28:29], v[8:9], v[212:213], v[28:29] op_sel_hi:[1,0,1]
	v_pk_fma_f32 v[26:27], v[10:11], v[212:213], v[26:27] op_sel:[0,1,0]
	v_pk_fma_f32 v[16:17], v[8:9], v[212:213], v[24:25] op_sel:[0,1,0]
	v_pk_fma_f32 v[24:25], v[10:11], v[214:215], v[90:91] op_sel_hi:[1,0,1]
	v_pk_fma_f32 v[18:19], v[8:9], v[214:215], v[88:89] op_sel_hi:[1,0,1]
	ds_read_b128 v[212:215], v13 offset:400
	s_waitcnt vmcnt(1) lgkmcnt(1)
	v_pk_fma_f32 v[82:83], v[6:7], v[208:209], v[82:83] op_sel_hi:[1,0,1]
	v_pk_fma_f32 v[80:81], v[4:5], v[208:209], v[80:81] op_sel_hi:[1,0,1]
	v_pk_fma_f32 v[78:79], v[6:7], v[208:209], v[78:79] op_sel:[0,1,0]
	v_pk_fma_f32 v[76:77], v[4:5], v[208:209], v[76:77] op_sel:[0,1,0]
	v_mov_b32_e32 v208, v211
	v_pk_fma_f32 v[74:75], v[6:7], v[210:211], v[74:75] op_sel_hi:[1,0,1]
	v_pk_fma_f32 v[72:73], v[4:5], v[210:211], v[72:73] op_sel_hi:[1,0,1]
	v_pk_fma_f32 v[70:71], v[6:7], v[208:209], v[70:71] op_sel_hi:[1,0,1]
	v_pk_fma_f32 v[68:69], v[4:5], v[208:209], v[68:69] op_sel_hi:[1,0,1]
	ds_read_b128 v[208:211], v13 offset:416
	s_waitcnt lgkmcnt(1)
	v_pk_fma_f32 v[66:67], v[6:7], v[212:213], v[66:67] op_sel_hi:[1,0,1]
	v_pk_fma_f32 v[64:65], v[4:5], v[212:213], v[64:65] op_sel_hi:[1,0,1]
	v_pk_fma_f32 v[62:63], v[6:7], v[212:213], v[62:63] op_sel:[0,1,0]
	v_pk_fma_f32 v[60:61], v[4:5], v[212:213], v[60:61] op_sel:[0,1,0]
	v_mov_b32_e32 v212, v215
	v_pk_fma_f32 v[58:59], v[6:7], v[214:215], v[58:59] op_sel_hi:[1,0,1]
	v_pk_fma_f32 v[56:57], v[4:5], v[214:215], v[56:57] op_sel_hi:[1,0,1]
	v_pk_fma_f32 v[54:55], v[6:7], v[212:213], v[54:55] op_sel_hi:[1,0,1]
	v_pk_fma_f32 v[48:49], v[4:5], v[212:213], v[48:49] op_sel_hi:[1,0,1]
	ds_read_b128 v[212:215], v13 offset:432
	s_waitcnt lgkmcnt(1)
	v_pk_fma_f32 v[52:53], v[6:7], v[208:209], v[52:53] op_sel_hi:[1,0,1]
	v_pk_fma_f32 v[50:51], v[4:5], v[208:209], v[50:51] op_sel_hi:[1,0,1]
	v_pk_fma_f32 v[46:47], v[6:7], v[208:209], v[46:47] op_sel:[0,1,0]
	v_pk_fma_f32 v[44:45], v[4:5], v[208:209], v[44:45] op_sel:[0,1,0]
	v_mov_b32_e32 v208, v211
	v_pk_fma_f32 v[42:43], v[6:7], v[210:211], v[42:43] op_sel_hi:[1,0,1]
	v_pk_fma_f32 v[40:41], v[4:5], v[210:211], v[40:41] op_sel_hi:[1,0,1]
	v_pk_fma_f32 v[38:39], v[6:7], v[208:209], v[38:39] op_sel_hi:[1,0,1]
	v_pk_fma_f32 v[36:37], v[4:5], v[208:209], v[36:37] op_sel_hi:[1,0,1]
	ds_read_b128 v[208:211], v13 offset:448
	s_waitcnt lgkmcnt(1)
	v_pk_fma_f32 v[30:31], v[6:7], v[212:213], v[30:31] op_sel_hi:[1,0,1]
	v_pk_fma_f32 v[28:29], v[4:5], v[212:213], v[28:29] op_sel_hi:[1,0,1]
	v_pk_fma_f32 v[26:27], v[6:7], v[212:213], v[26:27] op_sel:[0,1,0]
	v_pk_fma_f32 v[8:9], v[4:5], v[212:213], v[16:17] op_sel:[0,1,0]
	v_pk_fma_f32 v[16:17], v[6:7], v[214:215], v[22:23] op_sel_hi:[1,0,1]
	v_pk_fma_f32 v[20:21], v[4:5], v[214:215], v[20:21] op_sel_hi:[1,0,1]
	v_mov_b32_e32 v214, v215
	v_pk_fma_f32 v[88:89], v[6:7], v[214:215], v[24:25] op_sel_hi:[1,0,1]
	v_pk_fma_f32 v[10:11], v[4:5], v[214:215], v[18:19] op_sel_hi:[1,0,1]
	ds_read_b128 v[212:215], v13 offset:464
	s_waitcnt vmcnt(0) lgkmcnt(1)
	v_pk_fma_f32 v[82:83], v[2:3], v[208:209], v[82:83] op_sel_hi:[1,0,1]
	v_pk_fma_f32 v[80:81], v[0:1], v[208:209], v[80:81] op_sel_hi:[1,0,1]
	v_pk_fma_f32 v[78:79], v[2:3], v[208:209], v[78:79] op_sel:[0,1,0]
	v_pk_fma_f32 v[76:77], v[0:1], v[208:209], v[76:77] op_sel:[0,1,0]
	v_mov_b32_e32 v208, v211
	v_pk_fma_f32 v[74:75], v[2:3], v[210:211], v[74:75] op_sel_hi:[1,0,1]
	v_pk_fma_f32 v[72:73], v[0:1], v[210:211], v[72:73] op_sel_hi:[1,0,1]
	v_pk_fma_f32 v[70:71], v[2:3], v[208:209], v[70:71] op_sel_hi:[1,0,1]
	v_pk_fma_f32 v[68:69], v[0:1], v[208:209], v[68:69] op_sel_hi:[1,0,1]
	ds_read_b128 v[208:211], v13 offset:480
	s_waitcnt lgkmcnt(1)
	v_pk_fma_f32 v[66:67], v[2:3], v[212:213], v[66:67] op_sel_hi:[1,0,1]
	v_pk_fma_f32 v[64:65], v[0:1], v[212:213], v[64:65] op_sel_hi:[1,0,1]
	v_pk_fma_f32 v[62:63], v[2:3], v[212:213], v[62:63] op_sel:[0,1,0]
	v_pk_fma_f32 v[60:61], v[0:1], v[212:213], v[60:61] op_sel:[0,1,0]
	v_mov_b32_e32 v212, v215
	v_pk_fma_f32 v[58:59], v[2:3], v[214:215], v[58:59] op_sel_hi:[1,0,1]
	v_pk_fma_f32 v[56:57], v[0:1], v[214:215], v[56:57] op_sel_hi:[1,0,1]
	v_pk_fma_f32 v[54:55], v[2:3], v[212:213], v[54:55] op_sel_hi:[1,0,1]
	v_pk_fma_f32 v[48:49], v[0:1], v[212:213], v[48:49] op_sel_hi:[1,0,1]
	ds_read_b128 v[212:215], v13 offset:496
	s_waitcnt lgkmcnt(1)
	v_pk_fma_f32 v[52:53], v[2:3], v[208:209], v[52:53] op_sel_hi:[1,0,1]
	v_pk_fma_f32 v[50:51], v[0:1], v[208:209], v[50:51] op_sel_hi:[1,0,1]
	v_pk_fma_f32 v[46:47], v[2:3], v[208:209], v[46:47] op_sel:[0,1,0]
	v_pk_fma_f32 v[44:45], v[0:1], v[208:209], v[44:45] op_sel:[0,1,0]
	v_mov_b32_e32 v208, v211
	v_pk_fma_f32 v[42:43], v[2:3], v[210:211], v[42:43] op_sel_hi:[1,0,1]
	v_pk_fma_f32 v[40:41], v[0:1], v[210:211], v[40:41] op_sel_hi:[1,0,1]
	v_pk_fma_f32 v[38:39], v[2:3], v[208:209], v[38:39] op_sel_hi:[1,0,1]
	v_pk_fma_f32 v[36:37], v[0:1], v[208:209], v[36:37] op_sel_hi:[1,0,1]
	s_waitcnt lgkmcnt(0)
	v_pk_fma_f32 v[30:31], v[2:3], v[212:213], v[30:31] op_sel_hi:[1,0,1]
	v_pk_fma_f32 v[28:29], v[0:1], v[212:213], v[28:29] op_sel_hi:[1,0,1]
	v_pk_fma_f32 v[26:27], v[2:3], v[212:213], v[26:27] op_sel:[0,1,0]
	v_pk_fma_f32 v[24:25], v[0:1], v[212:213], v[8:9] op_sel:[0,1,0]
	v_mov_b32_e32 v212, v215
	v_pk_fma_f32 v[22:23], v[2:3], v[214:215], v[16:17] op_sel_hi:[1,0,1]
	v_pk_fma_f32 v[20:21], v[0:1], v[214:215], v[20:21] op_sel_hi:[1,0,1]
	v_pk_fma_f32 v[18:19], v[2:3], v[212:213], v[88:89] op_sel_hi:[1,0,1]
	v_pk_fma_f32 v[16:17], v[0:1], v[212:213], v[10:11] op_sel_hi:[1,0,1]
	s_cbranch_scc0 .LBB0_510
; __device__ __forceinline__ unsigned cvt_pk_bf16(float lo, float hi) { unsigned r; asm volatile("v_cvt_pk_bf16_f32 %0, %1, %2" : "=v"(r) : "v"(lo), "v"(hi)); return r; }
; template <int LOGN>
; __device__ void hyena_filters(const Params& p, unsigned char* shm, int c0, int cstride) {
;     ...
;     for (int k = 0; k < 4; ++k) {
;       int c = c0 + k * cstride; if (c > 1023) c = 1023;
;       const float delta = fabsf(dmin_ + (float)c * ((dmax_ - dmin_) / 1023.0f));
;       f32x4 dec;
; #pragma unroll
;       for (int e = 0; e < 4; ++e) dec[e] = __expf(-(float)(t4 + e) * invL1 * delta);
; #pragma unroll
;       for (int f = 0; f < 4; ++f) { const f32x4 v = acc[k * 4 + f] * dec; *(u32x2*)(FSb + (size_t)(k * 4 + f) * L + t4) = (u32x2){cvt_pk_bf16(v[0], v[1]), cvt_pk_bf16(v[2], v[3])}; }
	v_cvt_f32_i32_e32 v0, v12
	v_or_b32_e32 v3, 2, v12
	v_or_b32_e32 v1, 1, v12
	v_cvt_f32_i32_e32 v1, v1
	v_mul_f32_e32 v10, 0xb8800200, v0
	v_mul_f32_e64 v0, |v32|, v10
	v_mul_f32_e32 v0, 0x3fb8aa3b, v0
	v_exp_f32_e32 v2, v0
	v_cvt_f32_i32_e32 v0, v3
	v_mul_f32_e32 v11, 0xb8800200, v1
	v_mul_f32_e64 v1, |v32|, v11
	v_mul_f32_e32 v1, 0x3fb8aa3b, v1
	v_mul_f32_e32 v34, 0xb8800200, v0
	v_or_b32_e32 v0, 3, v12
	v_cvt_f32_i32_e32 v0, v0
	v_mul_f32_e64 v3, |v32|, v34
	v_mul_f32_e32 v3, 0x3fb8aa3b, v3
	v_exp_f32_e32 v4, v3
	v_mul_f32_e32 v35, 0xb8800200, v0
	v_mul_f32_e64 v0, |v32|, v35
	v_mul_f32_e32 v0, 0x3fb8aa3b, v0
	v_exp_f32_e32 v3, v1
	v_exp_f32_e32 v5, v0
	v_readlane_b32 s14, v253, 18
	v_ashrrev_i32_e32 v13, 31, v12
	v_readlane_b32 s15, v253, 19
	v_pk_mul_f32 v[8:9], v[2:3], v[80:81]
	v_pk_mul_f32 v[6:7], v[4:5], v[82:83]
	v_lshl_add_u64 v[0:1], v[12:13], 1, s[14:15]
	v_cvt_pk_bf16_f32 v8, v8, v9
	v_cvt_pk_bf16_f32 v9, v6, v7
	global_store_dwordx2 v[0:1], v[8:9], off
	v_pk_mul_f32 v[6:7], v[4:5], v[78:79]
	v_pk_mul_f32 v[8:9], v[2:3], v[76:77]
	s_mov_b32 s5, 0x10000
	v_cvt_pk_bf16_f32 v8, v8, v9
	v_cvt_pk_bf16_f32 v9, v6, v7
	v_add_co_u32_e32 v6, vcc, s78, v0
	s_mov_b64 s[14:15], 0x2000
	s_nop 0
	v_addc_co_u32_e32 v7, vcc, 0, v1, vcc
	global_store_dwordx2 v[6:7], v[8:9], off
	v_pk_mul_f32 v[6:7], v[4:5], v[74:75]
	v_pk_mul_f32 v[8:9], v[2:3], v[72:73]
	v_pk_mul_f32 v[4:5], v[4:5], v[70:71]
	v_cvt_pk_bf16_f32 v8, v8, v9
	v_cvt_pk_bf16_f32 v9, v6, v7
	v_add_co_u32_e32 v6, vcc, s5, v0
	v_pk_mul_f32 v[2:3], v[2:3], v[68:69]
	s_nop 0
	v_addc_co_u32_e32 v7, vcc, 0, v1, vcc
	global_store_dwordx2 v[6:7], v[8:9], off
	v_cvt_pk_bf16_f32 v2, v2, v3
	v_cvt_pk_bf16_f32 v3, v4, v5
	v_mul_f32_e64 v4, |v84|, v10
	v_mul_f32_e64 v5, |v84|, v11
	v_mul_f32_e64 v6, |v84|, v34
	v_mul_f32_e64 v7, |v84|, v35
	v_mul_f32_e32 v4, 0x3fb8aa3b, v4
	v_mul_f32_e32 v5, 0x3fb8aa3b, v5
	v_mul_f32_e32 v6, 0x3fb8aa3b, v6
	v_mul_f32_e32 v7, 0x3fb8aa3b, v7
	v_exp_f32_e32 v4, v4
	v_exp_f32_e32 v5, v5
	v_exp_f32_e32 v6, v6
	v_exp_f32_e32 v7, v7
	s_mov_b32 s5, 0x18000
	v_add_co_u32_e32 v8, vcc, s5, v0
	s_mov_b32 s5, 0x20000
	s_nop 0
	v_addc_co_u32_e32 v9, vcc, 0, v1, vcc
	global_store_dwordx2 v[8:9], v[2:3], off
	v_pk_mul_f32 v[2:3], v[6:7], v[66:67]
	v_pk_mul_f32 v[8:9], v[4:5], v[64:65]
	v_lshl_add_u64 v[14:15], v[14:15], 0, s[14:15]
	v_cvt_pk_bf16_f32 v8, v8, v9
	v_cvt_pk_bf16_f32 v9, v2, v3
	v_add_co_u32_e32 v2, vcc, s5, v0
	s_mov_b32 s5, 0x28000
	s_nop 0
	v_addc_co_u32_e32 v3, vcc, 0, v1, vcc
	global_store_dwordx2 v[2:3], v[8:9], off
	v_pk_mul_f32 v[2:3], v[6:7], v[62:63]
	v_pk_mul_f32 v[8:9], v[4:5], v[60:61]
	s_nop 0
	v_cvt_pk_bf16_f32 v8, v8, v9
	v_cvt_pk_bf16_f32 v9, v2, v3
	v_add_co_u32_e32 v2, vcc, s5, v0
	s_mov_b32 s5, 0x30000
	s_nop 0
	v_addc_co_u32_e32 v3, vcc, 0, v1, vcc
	global_store_dwordx2 v[2:3], v[8:9], off
	v_pk_mul_f32 v[2:3], v[6:7], v[58:59]
	v_pk_mul_f32 v[8:9], v[4:5], v[56:57]
	v_pk_mul_f32 v[4:5], v[4:5], v[48:49]
	v_cvt_pk_bf16_f32 v8, v8, v9
	v_cvt_pk_bf16_f32 v9, v2, v3
	v_add_co_u32_e32 v2, vcc, s5, v0
	s_mov_b32 s5, 0x38000
	s_nop 0
	v_addc_co_u32_e32 v3, vcc, 0, v1, vcc
	global_store_dwordx2 v[2:3], v[8:9], off
	v_pk_mul_f32 v[2:3], v[6:7], v[54:55]
	v_cvt_pk_bf16_f32 v4, v4, v5
	v_mul_f32_e64 v6, |v85|, v34
	v_cvt_pk_bf16_f32 v5, v2, v3
	v_mul_f32_e64 v2, |v85|, v10
	v_mul_f32_e64 v3, |v85|, v11
	v_mul_f32_e64 v7, |v85|, v35
	v_mul_f32_e32 v2, 0x3fb8aa3b, v2
	v_mul_f32_e32 v3, 0x3fb8aa3b, v3
	v_mul_f32_e32 v6, 0x3fb8aa3b, v6
	v_mul_f32_e32 v7, 0x3fb8aa3b, v7
	v_exp_f32_e32 v2, v2
	v_exp_f32_e32 v3, v3
	v_exp_f32_e32 v6, v6
	v_exp_f32_e32 v7, v7
	v_add_co_u32_e32 v8, vcc, s5, v0
	s_mov_b32 s5, 0x40000
	s_nop 0
	v_addc_co_u32_e32 v9, vcc, 0, v1, vcc
	global_store_dwordx2 v[8:9], v[4:5], off
	v_pk_mul_f32 v[4:5], v[6:7], v[52:53]
	v_pk_mul_f32 v[8:9], v[2:3], v[50:51]
	s_nop 0
	v_cvt_pk_bf16_f32 v8, v8, v9
	v_cvt_pk_bf16_f32 v9, v4, v5
	v_add_co_u32_e32 v4, vcc, s5, v0
	s_mov_b32 s5, 0x48000
	s_nop 0
	v_addc_co_u32_e32 v5, vcc, 0, v1, vcc
	global_store_dwordx2 v[4:5], v[8:9], off
	v_pk_mul_f32 v[4:5], v[6:7], v[46:47]
	v_pk_mul_f32 v[8:9], v[2:3], v[44:45]
	s_nop 0
	v_cvt_pk_bf16_f32 v8, v8, v9
	v_cvt_pk_bf16_f32 v9, v4, v5
	v_add_co_u32_e32 v4, vcc, s5, v0
	s_mov_b32 s5, 0x50000
	s_nop 0
	v_addc_co_u32_e32 v5, vcc, 0, v1, vcc
	global_store_dwordx2 v[4:5], v[8:9], off
	v_pk_mul_f32 v[4:5], v[6:7], v[42:43]
	v_pk_mul_f32 v[8:9], v[2:3], v[40:41]
	v_pk_mul_f32 v[2:3], v[2:3], v[36:37]
	v_cvt_pk_bf16_f32 v8, v8, v9
	v_cvt_pk_bf16_f32 v9, v4, v5
	v_add_co_u32_e32 v4, vcc, s5, v0
	s_mov_b32 s5, 0x58000
	s_nop 0
	v_addc_co_u32_e32 v5, vcc, 0, v1, vcc
	global_store_dwordx2 v[4:5], v[8:9], off
	v_pk_mul_f32 v[4:5], v[6:7], v[38:39]
	v_cvt_pk_bf16_f32 v2, v2, v3
	v_mul_f32_e64 v6, |v86|, v34
	v_cvt_pk_bf16_f32 v3, v4, v5
	v_mul_f32_e64 v4, |v86|, v10
	v_mul_f32_e64 v5, |v86|, v11
	v_mul_f32_e64 v7, |v86|, v35
	v_mul_f32_e32 v4, 0x3fb8aa3b, v4
	v_mul_f32_e32 v5, 0x3fb8aa3b, v5
	v_mul_f32_e32 v6, 0x3fb8aa3b, v6
	v_mul_f32_e32 v7, 0x3fb8aa3b, v7
	v_exp_f32_e32 v4, v4
	v_exp_f32_e32 v5, v5
	v_exp_f32_e32 v6, v6
	v_exp_f32_e32 v7, v7
	v_add_co_u32_e32 v8, vcc, s5, v0
	s_mov_b32 s5, 0x60000
	s_nop 0
	v_addc_co_u32_e32 v9, vcc, 0, v1, vcc
	global_store_dwordx2 v[8:9], v[2:3], off
	v_pk_mul_f32 v[2:3], v[6:7], v[30:31]
	v_pk_mul_f32 v[8:9], v[4:5], v[28:29]
	s_nop 0
	v_cvt_pk_bf16_f32 v8, v8, v9
	v_cvt_pk_bf16_f32 v9, v2, v3
	v_add_co_u32_e32 v2, vcc, s5, v0
	s_mov_b32 s5, 0x68000
	s_nop 0
	v_addc_co_u32_e32 v3, vcc, 0, v1, vcc
	global_store_dwordx2 v[2:3], v[8:9], off
	v_pk_mul_f32 v[2:3], v[6:7], v[26:27]
	v_pk_mul_f32 v[8:9], v[4:5], v[24:25]
	s_nop 0
	v_cvt_pk_bf16_f32 v8, v8, v9
	v_cvt_pk_bf16_f32 v9, v2, v3
	v_add_co_u32_e32 v2, vcc, s5, v0
	s_mov_b32 s5, 0x70000
	s_nop 0
	v_addc_co_u32_e32 v3, vcc, 0, v1, vcc
	global_store_dwordx2 v[2:3], v[8:9], off
	v_pk_mul_f32 v[2:3], v[6:7], v[22:23]
	v_pk_mul_f32 v[8:9], v[4:5], v[20:21]
	v_pk_mul_f32 v[4:5], v[4:5], v[16:17]
	v_cvt_pk_bf16_f32 v8, v8, v9
	v_cvt_pk_bf16_f32 v9, v2, v3
	v_add_co_u32_e32 v2, vcc, s5, v0
	s_movk_i32 s5, 0x37ff
	s_nop 0
	v_addc_co_u32_e32 v3, vcc, 0, v1, vcc
	v_add_co_u32_e32 v0, vcc, 0x78000, v0
	global_store_dwordx2 v[2:3], v[8:9], off
	s_nop 0
	v_addc_co_u32_e32 v1, vcc, 0, v1, vcc
	v_pk_mul_f32 v[2:3], v[6:7], v[18:19]
	v_cvt_pk_bf16_f32 v4, v4, v5
	v_cmp_lt_i32_e32 vcc, s5, v12
	v_cvt_pk_bf16_f32 v5, v2, v3
	global_store_dwordx2 v[0:1], v[4:5], off
	v_add_u32_e32 v0, 0x800, v12
	s_or_b64 s[20:21], vcc, s[20:21]
	v_mov_b32_e32 v12, v0
	s_andn2_b64 exec, exec, s[20:21]
	s_cbranch_execnz .LBB0_509

; template <int LOGN>
; __device__ void hyena_filters(const Params& p, unsigned char* shm, int c0, int cstride) {
;     ...
;     for (int j0 = 0; j0 < 64; j0 += 8) {
;       f32x4 hv[8];
; #pragma unroll
;       for (int j = 0; j < 8; ++j) hv[j] = *(const f32x4*)(h3T + (size_t)(j0 + j) * L + t4);
; #pragma unroll
;       for (int j = 0; j < 8; ++j) {
;         const f32x4* wp = (const f32x4*)(sW + (j0 + j) * 16);
; #pragma unroll
;         for (int q = 0; q < 4; ++q) { const f32x4 w = wp[q]; acc[q * 4] += hv[j] * w[0]; acc[q * 4 + 1] += hv[j] * w[1]; acc[q * 4 + 2] += hv[j] * w[2]; acc[q * 4 + 3] += hv[j] * w[3]; }
;       }
.LBB0_936:
	s_mov_b32 s11, 0xfffc8000
	v_add_co_u32_e32 v0, vcc, s11, v34
	s_mov_b32 s11, 0xfffd8000
	s_nop 0
	v_addc_co_u32_e32 v1, vcc, -1, v35, vcc
	global_load_dwordx4 v[88:91], v[0:1], off
	v_add_co_u32_e32 v0, vcc, s24, v34
	v_mov_b32_e32 v13, s7
	s_nop 0
	v_addc_co_u32_e32 v1, vcc, -1, v35, vcc
	global_load_dwordx4 v[92:95], v[0:1], off
	v_add_co_u32_e32 v0, vcc, s11, v34
	s_mov_b32 s11, 0xfffe8000
	s_nop 0
	v_addc_co_u32_e32 v1, vcc, -1, v35, vcc
	global_load_dwordx4 v[96:99], v[0:1], off
	v_add_co_u32_e32 v0, vcc, s25, v34
	s_add_i32 s5, s5, 8
	s_nop 0
	v_addc_co_u32_e32 v1, vcc, -1, v35, vcc
	global_load_dwordx4 v[100:103], v[0:1], off
	v_add_co_u32_e32 v0, vcc, s11, v34
	s_movk_i32 s11, 0x8000
	s_nop 0
	v_addc_co_u32_e32 v1, vcc, -1, v35, vcc
	global_load_dwordx4 v[104:107], v[0:1], off
	v_add_co_u32_e32 v0, vcc, s66, v34
	s_addk_i32 s7, 0x200
	s_nop 0
	v_addc_co_u32_e32 v1, vcc, -1, v35, vcc
	global_load_dwordx4 v[8:11], v[0:1], off
	v_add_co_u32_e32 v0, vcc, s11, v34
	s_mov_b64 s[14:15], 0x40000
	s_nop 0
	v_addc_co_u32_e32 v1, vcc, -1, v35, vcc
	global_load_dwordx4 v[4:7], v[0:1], off
	s_nop 0
	global_load_dwordx4 v[0:3], v[34:35], off
	ds_read_b128 v[108:111], v13
	ds_read_b128 v[112:115], v13 offset:16
	ds_read_b128 v[116:119], v13 offset:32
	ds_read_b128 v[120:123], v13 offset:48
	v_lshl_add_u64 v[34:35], v[34:35], 0, s[14:15]
	s_cmp_gt_u32 s5, 55
	s_waitcnt vmcnt(7) lgkmcnt(3)
	v_pk_fma_f32 v[82:83], v[90:91], v[108:109], v[82:83] op_sel_hi:[1,0,1]
	v_pk_fma_f32 v[80:81], v[88:89], v[108:109], v[80:81] op_sel_hi:[1,0,1]
	v_pk_fma_f32 v[78:79], v[90:91], v[108:109], v[78:79] op_sel:[0,1,0]
	v_pk_fma_f32 v[76:77], v[88:89], v[108:109], v[76:77] op_sel:[0,1,0]
	v_mov_b32_e32 v108, v111
	v_pk_fma_f32 v[70:71], v[90:91], v[108:109], v[70:71] op_sel_hi:[1,0,1]
	v_pk_fma_f32 v[68:69], v[88:89], v[108:109], v[68:69] op_sel_hi:[1,0,1]
	s_waitcnt lgkmcnt(2)
	v_mov_b32_e32 v108, v115
	v_pk_fma_f32 v[54:55], v[90:91], v[108:109], v[54:55] op_sel_hi:[1,0,1]
	v_pk_fma_f32 v[48:49], v[88:89], v[108:109], v[48:49] op_sel_hi:[1,0,1]
	s_waitcnt lgkmcnt(1)
	v_mov_b32_e32 v108, v119
	v_pk_fma_f32 v[38:39], v[90:91], v[108:109], v[38:39] op_sel_hi:[1,0,1]
	v_pk_fma_f32 v[36:37], v[88:89], v[108:109], v[36:37] op_sel_hi:[1,0,1]
	s_waitcnt lgkmcnt(0)
	v_mov_b32_e32 v108, v123
	v_pk_fma_f32 v[74:75], v[90:91], v[110:111], v[74:75] op_sel_hi:[1,0,1]
	v_pk_fma_f32 v[72:73], v[88:89], v[110:111], v[72:73] op_sel_hi:[1,0,1]
	v_pk_fma_f32 v[66:67], v[90:91], v[112:113], v[66:67] op_sel_hi:[1,0,1]
	v_pk_fma_f32 v[64:65], v[88:89], v[112:113], v[64:65] op_sel_hi:[1,0,1]
	v_pk_fma_f32 v[62:63], v[90:91], v[112:113], v[62:63] op_sel:[0,1,0]
	v_pk_fma_f32 v[60:61], v[88:89], v[112:113], v[60:61] op_sel:[0,1,0]
	v_pk_fma_f32 v[58:59], v[90:91], v[114:115], v[58:59] op_sel_hi:[1,0,1]
	v_pk_fma_f32 v[56:57], v[88:89], v[114:115], v[56:57] op_sel_hi:[1,0,1]
	v_pk_fma_f32 v[52:53], v[90:91], v[116:117], v[52:53] op_sel_hi:[1,0,1]
	v_pk_fma_f32 v[50:51], v[88:89], v[116:117], v[50:51] op_sel_hi:[1,0,1]
	v_pk_fma_f32 v[46:47], v[90:91], v[116:117], v[46:47] op_sel:[0,1,0]
	v_pk_fma_f32 v[44:45], v[88:89], v[116:117], v[44:45] op_sel:[0,1,0]
	v_pk_fma_f32 v[42:43], v[90:91], v[118:119], v[42:43] op_sel_hi:[1,0,1]
	v_pk_fma_f32 v[40:41], v[88:89], v[118:119], v[40:41] op_sel_hi:[1,0,1]
	v_pk_fma_f32 v[30:31], v[90:91], v[120:121], v[30:31] op_sel_hi:[1,0,1]
	v_pk_fma_f32 v[28:29], v[88:89], v[120:121], v[28:29] op_sel_hi:[1,0,1]
	v_pk_fma_f32 v[26:27], v[90:91], v[120:121], v[26:27] op_sel:[0,1,0]
	v_pk_fma_f32 v[24:25], v[88:89], v[120:121], v[24:25] op_sel:[0,1,0]
	v_pk_fma_f32 v[22:23], v[90:91], v[122:123], v[22:23] op_sel_hi:[1,0,1]
	v_pk_fma_f32 v[20:21], v[88:89], v[122:123], v[20:21] op_sel_hi:[1,0,1]
	v_pk_fma_f32 v[90:91], v[90:91], v[108:109], v[18:19] op_sel_hi:[1,0,1]
	v_pk_fma_f32 v[88:89], v[88:89], v[108:109], v[16:17] op_sel_hi:[1,0,1]
	ds_read_b128 v[208:211], v13 offset:64
	ds_read_b128 v[212:215], v13 offset:80
	s_waitcnt vmcnt(6) lgkmcnt(1)
	v_pk_fma_f32 v[82:83], v[94:95], v[208:209], v[82:83] op_sel_hi:[1,0,1]
	v_pk_fma_f32 v[80:81], v[92:93], v[208:209], v[80:81] op_sel_hi:[1,0,1]
	v_pk_fma_f32 v[78:79], v[94:95], v[208:209], v[78:79] op_sel:[0,1,0]
	v_pk_fma_f32 v[76:77], v[92:93], v[208:209], v[76:77] op_sel:[0,1,0]
	v_mov_b32_e32 v208, v211
	v_pk_fma_f32 v[74:75], v[94:95], v[210:211], v[74:75] op_sel_hi:[1,0,1]
	v_pk_fma_f32 v[72:73], v[92:93], v[210:211], v[72:73] op_sel_hi:[1,0,1]
	v_pk_fma_f32 v[70:71], v[94:95], v[208:209], v[70:71] op_sel_hi:[1,0,1]
	v_pk_fma_f32 v[68:69], v[92:93], v[208:209], v[68:69] op_sel_hi:[1,0,1]
	ds_read_b128 v[208:211], v13 offset:96
	s_waitcnt lgkmcnt(1)
	v_pk_fma_f32 v[66:67], v[94:95], v[212:213], v[66:67] op_sel_hi:[1,0,1]
	v_pk_fma_f32 v[64:65], v[92:93], v[212:213], v[64:65] op_sel_hi:[1,0,1]
	v_pk_fma_f32 v[62:63], v[94:95], v[212:213], v[62:63] op_sel:[0,1,0]
	v_pk_fma_f32 v[60:61], v[92:93], v[212:213], v[60:61] op_sel:[0,1,0]
	v_mov_b32_e32 v212, v215
	v_pk_fma_f32 v[58:59], v[94:95], v[214:215], v[58:59] op_sel_hi:[1,0,1]
	v_pk_fma_f32 v[56:57], v[92:93], v[214:215], v[56:57] op_sel_hi:[1,0,1]
	v_pk_fma_f32 v[54:55], v[94:95], v[212:213], v[54:55] op_sel_hi:[1,0,1]
	v_pk_fma_f32 v[48:49], v[92:93], v[212:213], v[48:49] op_sel_hi:[1,0,1]
	ds_read_b128 v[212:215], v13 offset:112
	s_waitcnt lgkmcnt(1)
; template <int LOGN>
; __device__ void hyena_filters(const Params& p, unsigned char* shm, int c0, int cstride) {
;     ...
;       for (int j = 0; j < 8; ++j) {
;         const f32x4* wp = (const f32x4*)(sW + (j0 + j) * 16);
; #pragma unroll
;         for (int q = 0; q < 4; ++q) { const f32x4 w = wp[q]; acc[q * 4] += hv[j] * w[0]; acc[q * 4 + 1] += hv[j] * w[1]; acc[q * 4 + 2] += hv[j] * w[2]; acc[q * 4 + 3] += hv[j] * w[3]; }
;       }
	v_pk_fma_f32 v[52:53], v[94:95], v[208:209], v[52:53] op_sel_hi:[1,0,1]
	v_pk_fma_f32 v[50:51], v[92:93], v[208:209], v[50:51] op_sel_hi:[1,0,1]
	v_pk_fma_f32 v[46:47], v[94:95], v[208:209], v[46:47] op_sel:[0,1,0]
	v_pk_fma_f32 v[44:45], v[92:93], v[208:209], v[44:45] op_sel:[0,1,0]
	v_mov_b32_e32 v208, v211
	v_pk_fma_f32 v[42:43], v[94:95], v[210:211], v[42:43] op_sel_hi:[1,0,1]
	v_pk_fma_f32 v[40:41], v[92:93], v[210:211], v[40:41] op_sel_hi:[1,0,1]
	v_pk_fma_f32 v[38:39], v[94:95], v[208:209], v[38:39] op_sel_hi:[1,0,1]
	v_pk_fma_f32 v[36:37], v[92:93], v[208:209], v[36:37] op_sel_hi:[1,0,1]
	ds_read_b128 v[208:211], v13 offset:128
	s_waitcnt lgkmcnt(1)
	v_pk_fma_f32 v[30:31], v[94:95], v[212:213], v[30:31] op_sel_hi:[1,0,1]
	v_pk_fma_f32 v[28:29], v[92:93], v[212:213], v[28:29] op_sel_hi:[1,0,1]
	v_pk_fma_f32 v[26:27], v[94:95], v[212:213], v[26:27] op_sel:[0,1,0]
	v_pk_fma_f32 v[24:25], v[92:93], v[212:213], v[24:25] op_sel:[0,1,0]
	v_mov_b32_e32 v212, v215
	v_pk_fma_f32 v[22:23], v[94:95], v[214:215], v[22:23] op_sel_hi:[1,0,1]
	v_pk_fma_f32 v[20:21], v[92:93], v[214:215], v[20:21] op_sel_hi:[1,0,1]
	v_pk_fma_f32 v[90:91], v[94:95], v[212:213], v[90:91] op_sel_hi:[1,0,1]
	v_pk_fma_f32 v[88:89], v[92:93], v[212:213], v[88:89] op_sel_hi:[1,0,1]
	ds_read_b128 v[212:215], v13 offset:144
	s_waitcnt vmcnt(5) lgkmcnt(1)
	v_pk_fma_f32 v[82:83], v[98:99], v[208:209], v[82:83] op_sel_hi:[1,0,1]
	v_pk_fma_f32 v[80:81], v[96:97], v[208:209], v[80:81] op_sel_hi:[1,0,1]
	v_pk_fma_f32 v[78:79], v[98:99], v[208:209], v[78:79] op_sel:[0,1,0]
	v_pk_fma_f32 v[76:77], v[96:97], v[208:209], v[76:77] op_sel:[0,1,0]
	v_mov_b32_e32 v208, v211
	v_pk_fma_f32 v[74:75], v[98:99], v[210:211], v[74:75] op_sel_hi:[1,0,1]
	v_pk_fma_f32 v[72:73], v[96:97], v[210:211], v[72:73] op_sel_hi:[1,0,1]
	v_pk_fma_f32 v[70:71], v[98:99], v[208:209], v[70:71] op_sel_hi:[1,0,1]
	v_pk_fma_f32 v[68:69], v[96:97], v[208:209], v[68:69] op_sel_hi:[1,0,1]
	ds_read_b128 v[208:211], v13 offset:160
	s_waitcnt lgkmcnt(1)
	v_pk_fma_f32 v[66:67], v[98:99], v[212:213], v[66:67] op_sel_hi:[1,0,1]
	v_pk_fma_f32 v[64:65], v[96:97], v[212:213], v[64:65] op_sel_hi:[1,0,1]
	v_pk_fma_f32 v[62:63], v[98:99], v[212:213], v[62:63] op_sel:[0,1,0]
	v_pk_fma_f32 v[60:61], v[96:97], v[212:213], v[60:61] op_sel:[0,1,0]
	v_mov_b32_e32 v212, v215
	v_pk_fma_f32 v[58:59], v[98:99], v[214:215], v[58:59] op_sel_hi:[1,0,1]
	v_pk_fma_f32 v[56:57], v[96:97], v[214:215], v[56:57] op_sel_hi:[1,0,1]
	v_pk_fma_f32 v[54:55], v[98:99], v[212:213], v[54:55] op_sel_hi:[1,0,1]
	v_pk_fma_f32 v[48:49], v[96:97], v[212:213], v[48:49] op_sel_hi:[1,0,1]
	ds_read_b128 v[212:215], v13 offset:176
	s_waitcnt lgkmcnt(1)
	v_pk_fma_f32 v[52:53], v[98:99], v[208:209], v[52:53] op_sel_hi:[1,0,1]
	v_pk_fma_f32 v[50:51], v[96:97], v[208:209], v[50:51] op_sel_hi:[1,0,1]
	v_pk_fma_f32 v[46:47], v[98:99], v[208:209], v[46:47] op_sel:[0,1,0]
	v_pk_fma_f32 v[44:45], v[96:97], v[208:209], v[44:45] op_sel:[0,1,0]
	v_mov_b32_e32 v208, v211
	v_pk_fma_f32 v[42:43], v[98:99], v[210:211], v[42:43] op_sel_hi:[1,0,1]
	v_pk_fma_f32 v[40:41], v[96:97], v[210:211], v[40:41] op_sel_hi:[1,0,1]
	v_pk_fma_f32 v[38:39], v[98:99], v[208:209], v[38:39] op_sel_hi:[1,0,1]
	v_pk_fma_f32 v[36:37], v[96:97], v[208:209], v[36:37] op_sel_hi:[1,0,1]
	ds_read_b128 v[208:211], v13 offset:192
	s_waitcnt lgkmcnt(1)
	v_pk_fma_f32 v[30:31], v[98:99], v[212:213], v[30:31] op_sel_hi:[1,0,1]
	v_pk_fma_f32 v[28:29], v[96:97], v[212:213], v[28:29] op_sel_hi:[1,0,1]
	v_pk_fma_f32 v[26:27], v[98:99], v[212:213], v[26:27] op_sel:[0,1,0]
	v_pk_fma_f32 v[24:25], v[96:97], v[212:213], v[24:25] op_sel:[0,1,0]
	v_mov_b32_e32 v212, v215
	v_pk_fma_f32 v[22:23], v[98:99], v[214:215], v[22:23] op_sel_hi:[1,0,1]
	v_pk_fma_f32 v[20:21], v[96:97], v[214:215], v[20:21] op_sel_hi:[1,0,1]
	v_pk_fma_f32 v[90:91], v[98:99], v[212:213], v[90:91] op_sel_hi:[1,0,1]
	v_pk_fma_f32 v[88:89], v[96:97], v[212:213], v[88:89] op_sel_hi:[1,0,1]
	ds_read_b128 v[212:215], v13 offset:208
	s_waitcnt vmcnt(4) lgkmcnt(1)
	v_pk_fma_f32 v[82:83], v[102:103], v[208:209], v[82:83] op_sel_hi:[1,0,1]
	v_pk_fma_f32 v[80:81], v[100:101], v[208:209], v[80:81] op_sel_hi:[1,0,1]
	v_pk_fma_f32 v[78:79], v[102:103], v[208:209], v[78:79] op_sel:[0,1,0]
	v_pk_fma_f32 v[76:77], v[100:101], v[208:209], v[76:77] op_sel:[0,1,0]
	v_mov_b32_e32 v208, v211
	v_pk_fma_f32 v[74:75], v[102:103], v[210:211], v[74:75] op_sel_hi:[1,0,1]
	v_pk_fma_f32 v[72:73], v[100:101], v[210:211], v[72:73] op_sel_hi:[1,0,1]
	v_pk_fma_f32 v[70:71], v[102:103], v[208:209], v[70:71] op_sel_hi:[1,0,1]
	v_pk_fma_f32 v[68:69], v[100:101], v[208:209], v[68:69] op_sel_hi:[1,0,1]
	ds_read_b128 v[208:211], v13 offset:224
	s_waitcnt lgkmcnt(1)
	v_pk_fma_f32 v[66:67], v[102:103], v[212:213], v[66:67] op_sel_hi:[1,0,1]
	v_pk_fma_f32 v[64:65], v[100:101], v[212:213], v[64:65] op_sel_hi:[1,0,1]
	v_pk_fma_f32 v[62:63], v[102:103], v[212:213], v[62:63] op_sel:[0,1,0]
	v_pk_fma_f32 v[60:61], v[100:101], v[212:213], v[60:61] op_sel:[0,1,0]
	v_mov_b32_e32 v212, v215
	v_pk_fma_f32 v[58:59], v[102:103], v[214:215], v[58:59] op_sel_hi:[1,0,1]
	v_pk_fma_f32 v[56:57], v[100:101], v[214:215], v[56:57] op_sel_hi:[1,0,1]
	v_pk_fma_f32 v[54:55], v[102:103], v[212:213], v[54:55] op_sel_hi:[1,0,1]
	v_pk_fma_f32 v[48:49], v[100:101], v[212:213], v[48:49] op_sel_hi:[1,0,1]
	ds_read_b128 v[212:215], v13 offset:240
	s_waitcnt lgkmcnt(1)
; template <int LOGN>
; __device__ void hyena_filters(const Params& p, unsigned char* shm, int c0, int cstride) {
;     ...
;       for (int j = 0; j < 8; ++j) {
;         const f32x4* wp = (const f32x4*)(sW + (j0 + j) * 16);
; #pragma unroll
;         for (int q = 0; q < 4; ++q) { const f32x4 w = wp[q]; acc[q * 4] += hv[j] * w[0]; acc[q * 4 + 1] += hv[j] * w[1]; acc[q * 4 + 2] += hv[j] * w[2]; acc[q * 4 + 3] += hv[j] * w[3]; }
;       }
	v_pk_fma_f32 v[52:53], v[102:103], v[208:209], v[52:53] op_sel_hi:[1,0,1]
	v_pk_fma_f32 v[50:51], v[100:101], v[208:209], v[50:51] op_sel_hi:[1,0,1]
	v_pk_fma_f32 v[46:47], v[102:103], v[208:209], v[46:47] op_sel:[0,1,0]
	v_pk_fma_f32 v[44:45], v[100:101], v[208:209], v[44:45] op_sel:[0,1,0]
	v_mov_b32_e32 v208, v211
	v_pk_fma_f32 v[42:43], v[102:103], v[210:211], v[42:43] op_sel_hi:[1,0,1]
	v_pk_fma_f32 v[40:41], v[100:101], v[210:211], v[40:41] op_sel_hi:[1,0,1]
	v_pk_fma_f32 v[38:39], v[102:103], v[208:209], v[38:39] op_sel_hi:[1,0,1]
	v_pk_fma_f32 v[36:37], v[100:101], v[208:209], v[36:37] op_sel_hi:[1,0,1]
	ds_read_b128 v[208:211], v13 offset:256
	s_waitcnt lgkmcnt(1)
	v_pk_fma_f32 v[30:31], v[102:103], v[212:213], v[30:31] op_sel_hi:[1,0,1]
	v_pk_fma_f32 v[28:29], v[100:101], v[212:213], v[28:29] op_sel_hi:[1,0,1]
	v_pk_fma_f32 v[26:27], v[102:103], v[212:213], v[26:27] op_sel:[0,1,0]
	v_pk_fma_f32 v[24:25], v[100:101], v[212:213], v[24:25] op_sel:[0,1,0]
	v_mov_b32_e32 v212, v215
	v_pk_fma_f32 v[22:23], v[102:103], v[214:215], v[22:23] op_sel_hi:[1,0,1]
	v_pk_fma_f32 v[20:21], v[100:101], v[214:215], v[20:21] op_sel_hi:[1,0,1]
	v_pk_fma_f32 v[90:91], v[102:103], v[212:213], v[90:91] op_sel_hi:[1,0,1]
	v_pk_fma_f32 v[88:89], v[100:101], v[212:213], v[88:89] op_sel_hi:[1,0,1]
	ds_read_b128 v[212:215], v13 offset:272
	s_waitcnt vmcnt(3) lgkmcnt(1)
	v_pk_fma_f32 v[82:83], v[106:107], v[208:209], v[82:83] op_sel_hi:[1,0,1]
	v_pk_fma_f32 v[80:81], v[104:105], v[208:209], v[80:81] op_sel_hi:[1,0,1]
	v_pk_fma_f32 v[78:79], v[106:107], v[208:209], v[78:79] op_sel:[0,1,0]
	v_pk_fma_f32 v[76:77], v[104:105], v[208:209], v[76:77] op_sel:[0,1,0]
	v_mov_b32_e32 v208, v211
	v_pk_fma_f32 v[74:75], v[106:107], v[210:211], v[74:75] op_sel_hi:[1,0,1]
	v_pk_fma_f32 v[72:73], v[104:105], v[210:211], v[72:73] op_sel_hi:[1,0,1]
	v_pk_fma_f32 v[70:71], v[106:107], v[208:209], v[70:71] op_sel_hi:[1,0,1]
	v_pk_fma_f32 v[68:69], v[104:105], v[208:209], v[68:69] op_sel_hi:[1,0,1]
	ds_read_b128 v[208:211], v13 offset:288
	s_waitcnt lgkmcnt(1)
	v_pk_fma_f32 v[66:67], v[106:107], v[212:213], v[66:67] op_sel_hi:[1,0,1]
	v_pk_fma_f32 v[64:65], v[104:105], v[212:213], v[64:65] op_sel_hi:[1,0,1]
	v_pk_fma_f32 v[62:63], v[106:107], v[212:213], v[62:63] op_sel:[0,1,0]
	v_pk_fma_f32 v[60:61], v[104:105], v[212:213], v[60:61] op_sel:[0,1,0]
	v_mov_b32_e32 v212, v215
	v_pk_fma_f32 v[58:59], v[106:107], v[214:215], v[58:59] op_sel_hi:[1,0,1]
	v_pk_fma_f32 v[56:57], v[104:105], v[214:215], v[56:57] op_sel_hi:[1,0,1]
	v_pk_fma_f32 v[54:55], v[106:107], v[212:213], v[54:55] op_sel_hi:[1,0,1]
	v_pk_fma_f32 v[48:49], v[104:105], v[212:213], v[48:49] op_sel_hi:[1,0,1]
	ds_read_b128 v[212:215], v13 offset:304
	s_waitcnt lgkmcnt(1)
	v_pk_fma_f32 v[52:53], v[106:107], v[208:209], v[52:53] op_sel_hi:[1,0,1]
	v_pk_fma_f32 v[50:51], v[104:105], v[208:209], v[50:51] op_sel_hi:[1,0,1]
	v_pk_fma_f32 v[46:47], v[106:107], v[208:209], v[46:47] op_sel:[0,1,0]
	v_pk_fma_f32 v[44:45], v[104:105], v[208:209], v[44:45] op_sel:[0,1,0]
	v_mov_b32_e32 v208, v211
	v_pk_fma_f32 v[42:43], v[106:107], v[210:211], v[42:43] op_sel_hi:[1,0,1]
	v_pk_fma_f32 v[40:41], v[104:105], v[210:211], v[40:41] op_sel_hi:[1,0,1]
	v_pk_fma_f32 v[38:39], v[106:107], v[208:209], v[38:39] op_sel_hi:[1,0,1]
	v_pk_fma_f32 v[36:37], v[104:105], v[208:209], v[36:37] op_sel_hi:[1,0,1]
	ds_read_b128 v[208:211], v13 offset:320
	s_waitcnt lgkmcnt(1)
	v_pk_fma_f32 v[30:31], v[106:107], v[212:213], v[30:31] op_sel_hi:[1,0,1]
	v_pk_fma_f32 v[28:29], v[104:105], v[212:213], v[28:29] op_sel_hi:[1,0,1]
	v_pk_fma_f32 v[26:27], v[106:107], v[212:213], v[26:27] op_sel:[0,1,0]
	v_pk_fma_f32 v[24:25], v[104:105], v[212:213], v[24:25] op_sel:[0,1,0]
	v_mov_b32_e32 v212, v215
	v_pk_fma_f32 v[22:23], v[106:107], v[214:215], v[22:23] op_sel_hi:[1,0,1]
	v_pk_fma_f32 v[20:21], v[104:105], v[214:215], v[20:21] op_sel_hi:[1,0,1]
	v_pk_fma_f32 v[90:91], v[106:107], v[212:213], v[90:91] op_sel_hi:[1,0,1]
	v_pk_fma_f32 v[88:89], v[104:105], v[212:213], v[88:89] op_sel_hi:[1,0,1]
	ds_read_b128 v[212:215], v13 offset:336
	s_waitcnt vmcnt(2) lgkmcnt(1)
	v_pk_fma_f32 v[82:83], v[10:11], v[208:209], v[82:83] op_sel_hi:[1,0,1]
	v_pk_fma_f32 v[80:81], v[8:9], v[208:209], v[80:81] op_sel_hi:[1,0,1]
	v_pk_fma_f32 v[78:79], v[10:11], v[208:209], v[78:79] op_sel:[0,1,0]
	v_pk_fma_f32 v[76:77], v[8:9], v[208:209], v[76:77] op_sel:[0,1,0]
	v_mov_b32_e32 v208, v211
	v_pk_fma_f32 v[74:75], v[10:11], v[210:211], v[74:75] op_sel_hi:[1,0,1]
	v_pk_fma_f32 v[72:73], v[8:9], v[210:211], v[72:73] op_sel_hi:[1,0,1]
	v_pk_fma_f32 v[70:71], v[10:11], v[208:209], v[70:71] op_sel_hi:[1,0,1]
	v_pk_fma_f32 v[68:69], v[8:9], v[208:209], v[68:69] op_sel_hi:[1,0,1]
	ds_read_b128 v[208:211], v13 offset:352
	s_waitcnt lgkmcnt(1)
	v_pk_fma_f32 v[66:67], v[10:11], v[212:213], v[66:67] op_sel_hi:[1,0,1]
	v_pk_fma_f32 v[64:65], v[8:9], v[212:213], v[64:65] op_sel_hi:[1,0,1]
	v_pk_fma_f32 v[62:63], v[10:11], v[212:213], v[62:63] op_sel:[0,1,0]
	v_pk_fma_f32 v[60:61], v[8:9], v[212:213], v[60:61] op_sel:[0,1,0]
	v_mov_b32_e32 v212, v215
	v_pk_fma_f32 v[58:59], v[10:11], v[214:215], v[58:59] op_sel_hi:[1,0,1]
	v_pk_fma_f32 v[56:57], v[8:9], v[214:215], v[56:57] op_sel_hi:[1,0,1]
	v_pk_fma_f32 v[54:55], v[10:11], v[212:213], v[54:55] op_sel_hi:[1,0,1]
	v_pk_fma_f32 v[48:49], v[8:9], v[212:213], v[48:49] op_sel_hi:[1,0,1]
	ds_read_b128 v[212:215], v13 offset:368
	s_waitcnt lgkmcnt(1)
; template <int LOGN>
; __device__ void hyena_filters(const Params& p, unsigned char* shm, int c0, int cstride) {
;     ...
;       for (int j = 0; j < 8; ++j) {
;         const f32x4* wp = (const f32x4*)(sW + (j0 + j) * 16);
; #pragma unroll
;         for (int q = 0; q < 4; ++q) { const f32x4 w = wp[q]; acc[q * 4] += hv[j] * w[0]; acc[q * 4 + 1] += hv[j] * w[1]; acc[q * 4 + 2] += hv[j] * w[2]; acc[q * 4 + 3] += hv[j] * w[3]; }
;       }
	v_pk_fma_f32 v[52:53], v[10:11], v[208:209], v[52:53] op_sel_hi:[1,0,1]
	v_pk_fma_f32 v[50:51], v[8:9], v[208:209], v[50:51] op_sel_hi:[1,0,1]
	v_pk_fma_f32 v[46:47], v[10:11], v[208:209], v[46:47] op_sel:[0,1,0]
	v_pk_fma_f32 v[44:45], v[8:9], v[208:209], v[44:45] op_sel:[0,1,0]
	v_mov_b32_e32 v208, v211
	v_pk_fma_f32 v[42:43], v[10:11], v[210:211], v[42:43] op_sel_hi:[1,0,1]
	v_pk_fma_f32 v[40:41], v[8:9], v[210:211], v[40:41] op_sel_hi:[1,0,1]
	v_pk_fma_f32 v[38:39], v[10:11], v[208:209], v[38:39] op_sel_hi:[1,0,1]
	v_pk_fma_f32 v[36:37], v[8:9], v[208:209], v[36:37] op_sel_hi:[1,0,1]
	ds_read_b128 v[208:211], v13 offset:384
	s_waitcnt lgkmcnt(1)
	v_pk_fma_f32 v[22:23], v[10:11], v[214:215], v[22:23] op_sel_hi:[1,0,1]
	v_pk_fma_f32 v[20:21], v[8:9], v[214:215], v[20:21] op_sel_hi:[1,0,1]
	v_mov_b32_e32 v214, v215
	v_pk_fma_f32 v[30:31], v[10:11], v[212:213], v[30:31] op_sel_hi:[1,0,1]
	v_pk_fma_f32 v[28:29], v[8:9], v[212:213], v[28:29] op_sel_hi:[1,0,1]
	v_pk_fma_f32 v[26:27], v[10:11], v[212:213], v[26:27] op_sel:[0,1,0]
	v_pk_fma_f32 v[16:17], v[8:9], v[212:213], v[24:25] op_sel:[0,1,0]
	v_pk_fma_f32 v[24:25], v[10:11], v[214:215], v[90:91] op_sel_hi:[1,0,1]
	v_pk_fma_f32 v[18:19], v[8:9], v[214:215], v[88:89] op_sel_hi:[1,0,1]
	ds_read_b128 v[212:215], v13 offset:400
	s_waitcnt vmcnt(1) lgkmcnt(1)
	v_pk_fma_f32 v[82:83], v[6:7], v[208:209], v[82:83] op_sel_hi:[1,0,1]
	v_pk_fma_f32 v[80:81], v[4:5], v[208:209], v[80:81] op_sel_hi:[1,0,1]
	v_pk_fma_f32 v[78:79], v[6:7], v[208:209], v[78:79] op_sel:[0,1,0]
	v_pk_fma_f32 v[76:77], v[4:5], v[208:209], v[76:77] op_sel:[0,1,0]
	v_mov_b32_e32 v208, v211
	v_pk_fma_f32 v[74:75], v[6:7], v[210:211], v[74:75] op_sel_hi:[1,0,1]
	v_pk_fma_f32 v[72:73], v[4:5], v[210:211], v[72:73] op_sel_hi:[1,0,1]
	v_pk_fma_f32 v[70:71], v[6:7], v[208:209], v[70:71] op_sel_hi:[1,0,1]
	v_pk_fma_f32 v[68:69], v[4:5], v[208:209], v[68:69] op_sel_hi:[1,0,1]
	ds_read_b128 v[208:211], v13 offset:416
	s_waitcnt lgkmcnt(1)
	v_pk_fma_f32 v[66:67], v[6:7], v[212:213], v[66:67] op_sel_hi:[1,0,1]
	v_pk_fma_f32 v[64:65], v[4:5], v[212:213], v[64:65] op_sel_hi:[1,0,1]
	v_pk_fma_f32 v[62:63], v[6:7], v[212:213], v[62:63] op_sel:[0,1,0]
	v_pk_fma_f32 v[60:61], v[4:5], v[212:213], v[60:61] op_sel:[0,1,0]
	v_mov_b32_e32 v212, v215
	v_pk_fma_f32 v[58:59], v[6:7], v[214:215], v[58:59] op_sel_hi:[1,0,1]
	v_pk_fma_f32 v[56:57], v[4:5], v[214:215], v[56:57] op_sel_hi:[1,0,1]
	v_pk_fma_f32 v[54:55], v[6:7], v[212:213], v[54:55] op_sel_hi:[1,0,1]
	v_pk_fma_f32 v[48:49], v[4:5], v[212:213], v[48:49] op_sel_hi:[1,0,1]
	ds_read_b128 v[212:215], v13 offset:432
	s_waitcnt lgkmcnt(1)
	v_pk_fma_f32 v[52:53], v[6:7], v[208:209], v[52:53] op_sel_hi:[1,0,1]
	v_pk_fma_f32 v[50:51], v[4:5], v[208:209], v[50:51] op_sel_hi:[1,0,1]
	v_pk_fma_f32 v[46:47], v[6:7], v[208:209], v[46:47] op_sel:[0,1,0]
	v_pk_fma_f32 v[44:45], v[4:5], v[208:209], v[44:45] op_sel:[0,1,0]
	v_mov_b32_e32 v208, v211
	v_pk_fma_f32 v[42:43], v[6:7], v[210:211], v[42:43] op_sel_hi:[1,0,1]
	v_pk_fma_f32 v[40:41], v[4:5], v[210:211], v[40:41] op_sel_hi:[1,0,1]
	v_pk_fma_f32 v[38:39], v[6:7], v[208:209], v[38:39] op_sel_hi:[1,0,1]
	v_pk_fma_f32 v[36:37], v[4:5], v[208:209], v[36:37] op_sel_hi:[1,0,1]
	ds_read_b128 v[208:211], v13 offset:448
	s_waitcnt lgkmcnt(1)
	v_pk_fma_f32 v[30:31], v[6:7], v[212:213], v[30:31] op_sel_hi:[1,0,1]
	v_pk_fma_f32 v[28:29], v[4:5], v[212:213], v[28:29] op_sel_hi:[1,0,1]
	v_pk_fma_f32 v[26:27], v[6:7], v[212:213], v[26:27] op_sel:[0,1,0]
	v_pk_fma_f32 v[8:9], v[4:5], v[212:213], v[16:17] op_sel:[0,1,0]
	v_pk_fma_f32 v[16:17], v[6:7], v[214:215], v[22:23] op_sel_hi:[1,0,1]
	v_pk_fma_f32 v[20:21], v[4:5], v[214:215], v[20:21] op_sel_hi:[1,0,1]
	v_mov_b32_e32 v214, v215
	v_pk_fma_f32 v[88:89], v[6:7], v[214:215], v[24:25] op_sel_hi:[1,0,1]
	v_pk_fma_f32 v[10:11], v[4:5], v[214:215], v[18:19] op_sel_hi:[1,0,1]
	ds_read_b128 v[212:215], v13 offset:464
	s_waitcnt vmcnt(0) lgkmcnt(1)
	v_pk_fma_f32 v[82:83], v[2:3], v[208:209], v[82:83] op_sel_hi:[1,0,1]
	v_pk_fma_f32 v[80:81], v[0:1], v[208:209], v[80:81] op_sel_hi:[1,0,1]
	v_pk_fma_f32 v[78:79], v[2:3], v[208:209], v[78:79] op_sel:[0,1,0]
	v_pk_fma_f32 v[76:77], v[0:1], v[208:209], v[76:77] op_sel:[0,1,0]
	v_mov_b32_e32 v208, v211
	v_pk_fma_f32 v[74:75], v[2:3], v[210:211], v[74:75] op_sel_hi:[1,0,1]
	v_pk_fma_f32 v[72:73], v[0:1], v[210:211], v[72:73] op_sel_hi:[1,0,1]
	v_pk_fma_f32 v[70:71], v[2:3], v[208:209], v[70:71] op_sel_hi:[1,0,1]
	v_pk_fma_f32 v[68:69], v[0:1], v[208:209], v[68:69] op_sel_hi:[1,0,1]
	ds_read_b128 v[208:211], v13 offset:480
	s_waitcnt lgkmcnt(1)
	v_pk_fma_f32 v[66:67], v[2:3], v[212:213], v[66:67] op_sel_hi:[1,0,1]
	v_pk_fma_f32 v[64:65], v[0:1], v[212:213], v[64:65] op_sel_hi:[1,0,1]
	v_pk_fma_f32 v[62:63], v[2:3], v[212:213], v[62:63] op_sel:[0,1,0]
	v_pk_fma_f32 v[60:61], v[0:1], v[212:213], v[60:61] op_sel:[0,1,0]
	v_mov_b32_e32 v212, v215
	v_pk_fma_f32 v[58:59], v[2:3], v[214:215], v[58:59] op_sel_hi:[1,0,1]
	v_pk_fma_f32 v[56:57], v[0:1], v[214:215], v[56:57] op_sel_hi:[1,0,1]
	v_pk_fma_f32 v[54:55], v[2:3], v[212:213], v[54:55] op_sel_hi:[1,0,1]
	v_pk_fma_f32 v[48:49], v[0:1], v[212:213], v[48:49] op_sel_hi:[1,0,1]
	ds_read_b128 v[212:215], v13 offset:496
	s_waitcnt lgkmcnt(1)
	v_pk_fma_f32 v[52:53], v[2:3], v[208:209], v[52:53] op_sel_hi:[1,0,1]
	v_pk_fma_f32 v[50:51], v[0:1], v[208:209], v[50:51] op_sel_hi:[1,0,1]
	v_pk_fma_f32 v[46:47], v[2:3], v[208:209], v[46:47] op_sel:[0,1,0]
	v_pk_fma_f32 v[44:45], v[0:1], v[208:209], v[44:45] op_sel:[0,1,0]
	v_mov_b32_e32 v208, v211
	v_pk_fma_f32 v[42:43], v[2:3], v[210:211], v[42:43] op_sel_hi:[1,0,1]
	v_pk_fma_f32 v[40:41], v[0:1], v[210:211], v[40:41] op_sel_hi:[1,0,1]
	v_pk_fma_f32 v[38:39], v[2:3], v[208:209], v[38:39] op_sel_hi:[1,0,1]
	v_pk_fma_f32 v[36:37], v[0:1], v[208:209], v[36:37] op_sel_hi:[1,0,1]
	s_waitcnt lgkmcnt(0)
	v_pk_fma_f32 v[30:31], v[2:3], v[212:213], v[30:31] op_sel_hi:[1,0,1]
	v_pk_fma_f32 v[28:29], v[0:1], v[212:213], v[28:29] op_sel_hi:[1,0,1]
	v_pk_fma_f32 v[26:27], v[2:3], v[212:213], v[26:27] op_sel:[0,1,0]
	v_pk_fma_f32 v[24:25], v[0:1], v[212:213], v[8:9] op_sel:[0,1,0]
	v_mov_b32_e32 v212, v215
	v_pk_fma_f32 v[22:23], v[2:3], v[214:215], v[16:17] op_sel_hi:[1,0,1]
	v_pk_fma_f32 v[20:21], v[0:1], v[214:215], v[20:21] op_sel_hi:[1,0,1]
	v_pk_fma_f32 v[18:19], v[2:3], v[212:213], v[88:89] op_sel_hi:[1,0,1]
	v_pk_fma_f32 v[16:17], v[0:1], v[212:213], v[10:11] op_sel_hi:[1,0,1]
	s_cbranch_scc0 .LBB0_936
; __device__ __forceinline__ unsigned cvt_pk_bf16(float lo, float hi) { unsigned r; asm volatile("v_cvt_pk_bf16_f32 %0, %1, %2" : "=v"(r) : "v"(lo), "v"(hi)); return r; }
; template <int LOGN>
; __device__ void hyena_filters(const Params& p, unsigned char* shm, int c0, int cstride) {
;     ...
;     for (int k = 0; k < 4; ++k) {
;       int c = c0 + k * cstride; if (c > 1023) c = 1023;
;       const float delta = fabsf(dmin_ + (float)c * ((dmax_ - dmin_) / 1023.0f));
;       f32x4 dec;
; #pragma unroll
;       for (int e = 0; e < 4; ++e) dec[e] = __expf(-(float)(t4 + e) * invL1 * delta);
; #pragma unroll
;       for (int f = 0; f < 4; ++f) { const f32x4 v = acc[k * 4 + f] * dec; *(u32x2*)(FSb + (size_t)(k * 4 + f) * L + t4) = (u32x2){cvt_pk_bf16(v[0], v[1]), cvt_pk_bf16(v[2], v[3])}; }
	v_cvt_f32_i32_e32 v0, v12
	v_or_b32_e32 v3, 2, v12
	v_or_b32_e32 v1, 1, v12
	v_cvt_f32_i32_e32 v1, v1
	v_mul_f32_e32 v10, 0xb9000400, v0
	v_mul_f32_e64 v0, |v32|, v10
	v_mul_f32_e32 v0, 0x3fb8aa3b, v0
	v_exp_f32_e32 v2, v0
	v_cvt_f32_i32_e32 v0, v3
	v_mul_f32_e32 v11, 0xb9000400, v1
	v_mul_f32_e64 v1, |v32|, v11
	v_mul_f32_e32 v1, 0x3fb8aa3b, v1
	v_mul_f32_e32 v34, 0xb9000400, v0
	v_or_b32_e32 v0, 3, v12
	v_cvt_f32_i32_e32 v0, v0
	v_mul_f32_e64 v3, |v32|, v34
	v_mul_f32_e32 v3, 0x3fb8aa3b, v3
	v_exp_f32_e32 v4, v3
	v_mul_f32_e32 v35, 0xb9000400, v0
	v_mul_f32_e64 v0, |v32|, v35
	v_mul_f32_e32 v0, 0x3fb8aa3b, v0
	v_exp_f32_e32 v3, v1
	v_exp_f32_e32 v5, v0
	v_readlane_b32 s14, v253, 18
	v_ashrrev_i32_e32 v13, 31, v12
	v_readlane_b32 s15, v253, 19
	v_pk_mul_f32 v[8:9], v[2:3], v[80:81]
	v_pk_mul_f32 v[6:7], v[4:5], v[82:83]
	v_lshl_add_u64 v[0:1], v[12:13], 1, s[14:15]
	v_cvt_pk_bf16_f32 v8, v8, v9
	v_cvt_pk_bf16_f32 v9, v6, v7
	global_store_dwordx2 v[0:1], v[8:9], off
	v_pk_mul_f32 v[6:7], v[4:5], v[78:79]
	v_pk_mul_f32 v[8:9], v[2:3], v[76:77]
	s_mov_b32 s5, 0xc000
	v_cvt_pk_bf16_f32 v8, v8, v9
	v_cvt_pk_bf16_f32 v9, v6, v7
	v_add_co_u32_e32 v6, vcc, s90, v0
	s_mov_b64 s[14:15], 0x2000
	s_nop 0
	v_addc_co_u32_e32 v7, vcc, 0, v1, vcc
	global_store_dwordx2 v[6:7], v[8:9], off
	v_pk_mul_f32 v[6:7], v[4:5], v[74:75]
	v_pk_mul_f32 v[8:9], v[2:3], v[72:73]
	v_pk_mul_f32 v[4:5], v[4:5], v[70:71]
	v_cvt_pk_bf16_f32 v8, v8, v9
	v_cvt_pk_bf16_f32 v9, v6, v7
	v_add_co_u32_e32 v6, vcc, s78, v0
	v_pk_mul_f32 v[2:3], v[2:3], v[68:69]
	s_nop 0
	v_addc_co_u32_e32 v7, vcc, 0, v1, vcc
	global_store_dwordx2 v[6:7], v[8:9], off
	v_cvt_pk_bf16_f32 v2, v2, v3
	v_cvt_pk_bf16_f32 v3, v4, v5
	v_mul_f32_e64 v4, |v84|, v10
	v_mul_f32_e64 v5, |v84|, v11
	v_mul_f32_e64 v6, |v84|, v34
	v_mul_f32_e64 v7, |v84|, v35
	v_mul_f32_e32 v4, 0x3fb8aa3b, v4
	v_mul_f32_e32 v5, 0x3fb8aa3b, v5
	v_mul_f32_e32 v6, 0x3fb8aa3b, v6
	v_mul_f32_e32 v7, 0x3fb8aa3b, v7
	v_exp_f32_e32 v4, v4
	v_exp_f32_e32 v5, v5
	v_exp_f32_e32 v6, v6
	v_exp_f32_e32 v7, v7
	v_add_co_u32_e32 v8, vcc, s5, v0
	s_mov_b32 s5, 0x10000
	s_nop 0
	v_addc_co_u32_e32 v9, vcc, 0, v1, vcc
	global_store_dwordx2 v[8:9], v[2:3], off
	v_pk_mul_f32 v[2:3], v[6:7], v[66:67]
	v_pk_mul_f32 v[8:9], v[4:5], v[64:65]
	v_lshl_add_u64 v[14:15], v[14:15], 0, s[14:15]
	v_cvt_pk_bf16_f32 v8, v8, v9
	v_cvt_pk_bf16_f32 v9, v2, v3
	v_add_co_u32_e32 v2, vcc, s5, v0
	s_mov_b32 s5, 0x14000
	s_nop 0
	v_addc_co_u32_e32 v3, vcc, 0, v1, vcc
	global_store_dwordx2 v[2:3], v[8:9], off
	v_pk_mul_f32 v[2:3], v[6:7], v[62:63]
	v_pk_mul_f32 v[8:9], v[4:5], v[60:61]
	s_nop 0
	v_cvt_pk_bf16_f32 v8, v8, v9
	v_cvt_pk_bf16_f32 v9, v2, v3
	v_add_co_u32_e32 v2, vcc, s5, v0
	s_mov_b32 s5, 0x18000
	s_nop 0
	v_addc_co_u32_e32 v3, vcc, 0, v1, vcc
	global_store_dwordx2 v[2:3], v[8:9], off
	v_pk_mul_f32 v[2:3], v[6:7], v[58:59]
	v_pk_mul_f32 v[8:9], v[4:5], v[56:57]
	v_pk_mul_f32 v[4:5], v[4:5], v[48:49]
	v_cvt_pk_bf16_f32 v8, v8, v9
	v_cvt_pk_bf16_f32 v9, v2, v3
	v_add_co_u32_e32 v2, vcc, s5, v0
	s_mov_b32 s5, 0x1c000
	s_nop 0
	v_addc_co_u32_e32 v3, vcc, 0, v1, vcc
	global_store_dwordx2 v[2:3], v[8:9], off
	v_pk_mul_f32 v[2:3], v[6:7], v[54:55]
	v_cvt_pk_bf16_f32 v4, v4, v5
	v_mul_f32_e64 v6, |v85|, v34
	v_cvt_pk_bf16_f32 v5, v2, v3
	v_mul_f32_e64 v2, |v85|, v10
	v_mul_f32_e64 v3, |v85|, v11
	v_mul_f32_e64 v7, |v85|, v35
	v_mul_f32_e32 v2, 0x3fb8aa3b, v2
	v_mul_f32_e32 v3, 0x3fb8aa3b, v3
	v_mul_f32_e32 v6, 0x3fb8aa3b, v6
	v_mul_f32_e32 v7, 0x3fb8aa3b, v7
	v_exp_f32_e32 v2, v2
	v_exp_f32_e32 v3, v3
	v_exp_f32_e32 v6, v6
	v_exp_f32_e32 v7, v7
	v_add_co_u32_e32 v8, vcc, s5, v0
	s_mov_b32 s5, 0x20000
	s_nop 0
	v_addc_co_u32_e32 v9, vcc, 0, v1, vcc
	global_store_dwordx2 v[8:9], v[4:5], off
	v_pk_mul_f32 v[4:5], v[6:7], v[52:53]
	v_pk_mul_f32 v[8:9], v[2:3], v[50:51]
	s_nop 0
	v_cvt_pk_bf16_f32 v8, v8, v9
	v_cvt_pk_bf16_f32 v9, v4, v5
	v_add_co_u32_e32 v4, vcc, s5, v0
	s_mov_b32 s5, 0x24000
	s_nop 0
	v_addc_co_u32_e32 v5, vcc, 0, v1, vcc
	global_store_dwordx2 v[4:5], v[8:9], off
	v_pk_mul_f32 v[4:5], v[6:7], v[46:47]
	v_pk_mul_f32 v[8:9], v[2:3], v[44:45]
	s_nop 0
	v_cvt_pk_bf16_f32 v8, v8, v9
	v_cvt_pk_bf16_f32 v9, v4, v5
	v_add_co_u32_e32 v4, vcc, s5, v0
	s_mov_b32 s5, 0x28000
	s_nop 0
	v_addc_co_u32_e32 v5, vcc, 0, v1, vcc
	global_store_dwordx2 v[4:5], v[8:9], off
	v_pk_mul_f32 v[4:5], v[6:7], v[42:43]
	v_pk_mul_f32 v[8:9], v[2:3], v[40:41]
	v_pk_mul_f32 v[2:3], v[2:3], v[36:37]
	v_cvt_pk_bf16_f32 v8, v8, v9
	v_cvt_pk_bf16_f32 v9, v4, v5
	v_add_co_u32_e32 v4, vcc, s5, v0
	s_mov_b32 s5, 0x2c000
	s_nop 0
	v_addc_co_u32_e32 v5, vcc, 0, v1, vcc
	global_store_dwordx2 v[4:5], v[8:9], off
	v_pk_mul_f32 v[4:5], v[6:7], v[38:39]
	v_cvt_pk_bf16_f32 v2, v2, v3
	v_mul_f32_e64 v6, |v86|, v34
	v_cvt_pk_bf16_f32 v3, v4, v5
	v_mul_f32_e64 v4, |v86|, v10
	v_mul_f32_e64 v5, |v86|, v11
	v_mul_f32_e64 v7, |v86|, v35
	v_mul_f32_e32 v4, 0x3fb8aa3b, v4
	v_mul_f32_e32 v5, 0x3fb8aa3b, v5
	v_mul_f32_e32 v6, 0x3fb8aa3b, v6
	v_mul_f32_e32 v7, 0x3fb8aa3b, v7
	v_exp_f32_e32 v4, v4
	v_exp_f32_e32 v5, v5
	v_exp_f32_e32 v6, v6
	v_exp_f32_e32 v7, v7
	v_add_co_u32_e32 v8, vcc, s5, v0
	s_mov_b32 s5, 0x30000
	s_nop 0
	v_addc_co_u32_e32 v9, vcc, 0, v1, vcc
	global_store_dwordx2 v[8:9], v[2:3], off
	v_pk_mul_f32 v[2:3], v[6:7], v[30:31]
	v_pk_mul_f32 v[8:9], v[4:5], v[28:29]
	s_nop 0
	v_cvt_pk_bf16_f32 v8, v8, v9
	v_cvt_pk_bf16_f32 v9, v2, v3
	v_add_co_u32_e32 v2, vcc, s5, v0
	s_mov_b32 s5, 0x34000
	s_nop 0
	v_addc_co_u32_e32 v3, vcc, 0, v1, vcc
	global_store_dwordx2 v[2:3], v[8:9], off
	v_pk_mul_f32 v[2:3], v[6:7], v[26:27]
	v_pk_mul_f32 v[8:9], v[4:5], v[24:25]
	s_nop 0
	v_cvt_pk_bf16_f32 v8, v8, v9
	v_cvt_pk_bf16_f32 v9, v2, v3
	v_add_co_u32_e32 v2, vcc, s5, v0
	s_mov_b32 s5, 0x38000
	s_nop 0
	v_addc_co_u32_e32 v3, vcc, 0, v1, vcc
	global_store_dwordx2 v[2:3], v[8:9], off
	v_pk_mul_f32 v[2:3], v[6:7], v[22:23]
	v_pk_mul_f32 v[8:9], v[4:5], v[20:21]
	v_pk_mul_f32 v[4:5], v[4:5], v[16:17]
	v_cvt_pk_bf16_f32 v8, v8, v9
	v_cvt_pk_bf16_f32 v9, v2, v3
	v_add_co_u32_e32 v2, vcc, s5, v0
	s_movk_i32 s5, 0x17ff
	s_nop 0
	v_addc_co_u32_e32 v3, vcc, 0, v1, vcc
	v_add_co_u32_e32 v0, vcc, 0x3c000, v0
	global_store_dwordx2 v[2:3], v[8:9], off
	s_nop 0
	v_addc_co_u32_e32 v1, vcc, 0, v1, vcc
	v_pk_mul_f32 v[2:3], v[6:7], v[18:19]
	v_cvt_pk_bf16_f32 v4, v4, v5
	v_cmp_lt_i32_e32 vcc, s5, v12
	v_cvt_pk_bf16_f32 v5, v2, v3
	global_store_dwordx2 v[0:1], v[4:5], off
	v_add_u32_e32 v0, 0x800, v12
	s_or_b64 s[20:21], vcc, s[20:21]
	v_mov_b32_e32 v12, v0
	s_andn2_b64 exec, exec, s[20:21]
	s_cbranch_execnz .LBB0_935

; __device__ __forceinline__ float bflo(unsigned w) { return __uint_as_float(w << 16); }
; __device__ __forceinline__ float bfhi(unsigned w) { return __uint_as_float(w & 0xffff0000u); }
; template <int MODE>
; __device__ void row_pass(const Params& p, const bf16_t* d, int ldd, const float* g0, const float* g1, bf16_t* xs, bf16_t* xn, float* out) {
;     ...
;   for (int row = wv; row < MT; row += nw) {
;     float xv[32];
;     if (MODE <= 1) {
;       const float* xr = xrow(p, row);
; #pragma unroll
;       for (int i = 0; i < 8; ++i) { const f32x4 t = *(const f32x4*)(xr + i * 256 + lane * 4); xv[i * 4] = t[0]; xv[i * 4 + 1] = t[1]; xv[i * 4 + 2] = t[2]; xv[i * 4 + 3] = t[3]; }
;     } else {
; #pragma unroll
;       for (int i = 0; i < 8; ++i) { const u32x2 t = *(const u32x2*)(xs + (size_t)row * DM + i * 256 + lane * 4); xv[i * 4] = bflo(t.x); xv[i * 4 + 1] = bfhi(t.x); xv[i * 4 + 2] = bflo(t.y); xv[i * 4 + 3] = bfhi(t.y); }
;     }
;     if (MODE != 0) {
;       float dv[32]; float ss = 0.f;
; #pragma unroll
;       for (int i = 0; i < 8; ++i) { const u32x2 t = *(const u32x2*)(d + (size_t)row * ldd + i * 256 + lane * 4);
;         dv[i * 4] = bflo(t.x); dv[i * 4 + 1] = bfhi(t.x); dv[i * 4 + 2] = bflo(t.y); dv[i * 4 + 3] = bfhi(t.y);
;         ss += dv[i * 4] * dv[i * 4] + dv[i * 4 + 1] * dv[i * 4 + 1] + dv[i * 4 + 2] * dv[i * 4 + 2] + dv[i * 4 + 3] * dv[i * 4 + 3]; }
;       ss = wave_sum(ss);
.LBB0_1250:
	v_cmp_gt_i32_e32 vcc, s78, v38
	v_add_u32_e32 v0, 0xffff8000, v38
	v_mov_b32_e32 v2, s39
	v_mov_b32_e32 v3, s37
	v_cndmask_b32_e32 v1, 0, v39, vcc
	v_cndmask_b32_e32 v0, v0, v38, vcc
	v_cndmask_b32_e32 v3, v2, v3, vcc
	v_mov_b32_e32 v2, s38
	v_mov_b32_e32 v4, s36
	v_cndmask_b32_e32 v2, v2, v4, vcc
	v_lshlrev_b64 v[0:1], 13, v[0:1]
	v_lshl_add_u64 v[0:1], v[2:3], 0, v[0:1]
	v_lshl_add_u64 v[0:1], v[0:1], 0, v[32:33]
	global_load_dwordx4 v[28:31], v[0:1], off
	global_load_dwordx4 v[24:27], v[0:1], off offset:1024
	global_load_dwordx4 v[20:23], v[0:1], off offset:2048
	global_load_dwordx4 v[16:19], v[0:1], off offset:3072
	v_add_co_u32_e32 v0, vcc, s5, v0
	v_lshl_add_u64 v[38:39], v[38:39], 0, s[20:21]
	s_nop 0
	v_addc_co_u32_e32 v1, vcc, 0, v1, vcc
	v_add_co_u32_e32 v64, vcc, s67, v60
	global_load_dwordx4 v[12:15], v[0:1], off
	global_load_dwordx4 v[8:11], v[0:1], off offset:1024
	global_load_dwordx4 v[4:7], v[0:1], off offset:2048
	s_nop 0
	global_load_dwordx4 v[0:3], v[0:1], off offset:3072
	v_addc_co_u32_e32 v65, vcc, -1, v61, vcc
	global_load_dwordx2 v[34:35], v[64:65], off
	v_add_co_u32_e32 v62, vcc, s60, v60
	s_nop 1
	v_addc_co_u32_e32 v63, vcc, -1, v61, vcc
	global_load_dwordx2 v[210:211], v[62:63], off offset:-3584
	global_load_dwordx2 v[212:213], v[62:63], off offset:-3072
	global_load_dwordx2 v[214:215], v[62:63], off offset:-2560
	global_load_dwordx2 v[216:217], v[62:63], off offset:-2048
	global_load_dwordx2 v[218:219], v[62:63], off offset:-1536
	global_load_dwordx2 v[220:221], v[62:63], off offset:-1024
	global_load_dwordx2 v[222:223], v[62:63], off offset:-512
	s_waitcnt vmcnt(7)
	v_lshlrev_b32_e32 v104, 16, v34
	v_and_b32_e32 v103, 0xffff0000, v34
	v_lshlrev_b32_e32 v101, 16, v35
	v_and_b32_e32 v99, 0xffff0000, v35
	v_mul_f32_e32 v36, v103, v103
	v_fmac_f32_e32 v36, v104, v104
	v_fmac_f32_e32 v36, v101, v101
	v_fmac_f32_e32 v36, v99, v99
	s_waitcnt vmcnt(6)
	v_and_b32_e32 v100, 0xffff0000, v210
	v_lshlrev_b32_e32 v102, 16, v210
	v_mul_f32_e32 v34, v100, v100
	v_lshlrev_b32_e32 v98, 16, v211
	v_fmac_f32_e32 v34, v102, v102
	v_and_b32_e32 v97, 0xffff0000, v211
	v_fmac_f32_e32 v34, v98, v98
	v_fmac_f32_e32 v34, v97, v97
	v_add_f32_e32 v36, v36, v34
	s_waitcnt vmcnt(5)
	v_and_b32_e32 v95, 0xffff0000, v212
	v_lshlrev_b32_e32 v96, 16, v212
	v_mul_f32_e32 v34, v95, v95
	v_lshlrev_b32_e32 v94, 16, v213
	v_fmac_f32_e32 v34, v96, v96
	v_and_b32_e32 v93, 0xffff0000, v213
	v_fmac_f32_e32 v34, v94, v94
	v_fmac_f32_e32 v34, v93, v93
	v_add_f32_e32 v36, v36, v34
	s_waitcnt vmcnt(4)
	v_and_b32_e32 v91, 0xffff0000, v214
	v_lshlrev_b32_e32 v92, 16, v214
	v_mul_f32_e32 v34, v91, v91
	v_lshlrev_b32_e32 v90, 16, v215
	v_fmac_f32_e32 v34, v92, v92
	v_and_b32_e32 v89, 0xffff0000, v215
	v_fmac_f32_e32 v34, v90, v90
	v_fmac_f32_e32 v34, v89, v89
	v_add_f32_e32 v66, v36, v34
	s_waitcnt vmcnt(2)
	v_and_b32_e32 v78, 0xffff0000, v216
	v_and_b32_e32 v79, 0xffff0000, v218
	v_lshlrev_b32_e32 v81, 16, v218
	v_lshlrev_b32_e32 v80, 16, v216
	v_lshlrev_b32_e32 v76, 16, v217
	v_and_b32_e32 v74, 0xffff0000, v217
	v_pk_mul_f32 v[34:35], v[78:79], v[78:79]
	v_lshlrev_b32_e32 v77, 16, v219
	v_pk_fma_f32 v[34:35], v[80:81], v[80:81], v[34:35]
	v_and_b32_e32 v75, 0xffff0000, v219
	v_pk_fma_f32 v[34:35], v[76:77], v[76:77], v[34:35]
	s_nop 0
	v_pk_fma_f32 v[34:35], v[74:75], v[74:75], v[34:35]
	s_nop 0
	v_add_f32_e32 v34, v66, v34
	v_add_f32_e32 v88, v34, v35
	s_waitcnt vmcnt(0)
	v_and_b32_e32 v70, 0xffff0000, v220
	v_and_b32_e32 v71, 0xffff0000, v222
	v_lshlrev_b32_e32 v73, 16, v222
	v_lshlrev_b32_e32 v72, 16, v220
	v_lshlrev_b32_e32 v68, 16, v221
	v_and_b32_e32 v66, 0xffff0000, v221
	v_pk_mul_f32 v[34:35], v[70:71], v[70:71]
	v_lshlrev_b32_e32 v69, 16, v223
	v_pk_fma_f32 v[34:35], v[72:73], v[72:73], v[34:35]
	v_and_b32_e32 v67, 0xffff0000, v223
	v_pk_fma_f32 v[34:35], v[68:69], v[68:69], v[34:35]
	s_nop 0
	v_pk_fma_f32 v[34:35], v[66:67], v[66:67], v[34:35]
	s_nop 0
	v_add_f32_e32 v34, v88, v34
	v_add_f32_e32 v34, v34, v35
	ds_bpermute_b32 v35, v82, v34
	s_waitcnt lgkmcnt(0)
	v_add_f32_e32 v34, v34, v35
	ds_bpermute_b32 v35, v83, v34
	s_waitcnt lgkmcnt(0)
	v_add_f32_e32 v34, v34, v35
	ds_bpermute_b32 v35, v84, v34
	s_waitcnt lgkmcnt(0)
	v_add_f32_e32 v34, v34, v35
	ds_bpermute_b32 v35, v85, v34
	s_waitcnt lgkmcnt(0)
	v_add_f32_e32 v34, v34, v35
	ds_bpermute_b32 v35, v86, v34
	s_waitcnt lgkmcnt(0)
	v_add_f32_e32 v34, v34, v35
	ds_bpermute_b32 v35, v87, v34
	s_waitcnt lgkmcnt(0)
	v_add_f32_e32 v34, v34, v35
	v_fmamk_f32 v34, v34, 0x3a000000, v131
	v_cmp_gt_f32_e32 vcc, s61, v34
	v_mul_f32_e32 v35, 0x4b800000, v34
	s_nop 0
	v_cndmask_b32_e32 v34, v34, v35, vcc
	v_rsq_f32_e32 v34, v34
	s_nop 0
	v_mul_f32_e32 v35, 0x45800000, v34
	v_cndmask_b32_e32 v34, v34, v35, vcc
	v_mul_f32_e32 v88, 0.5, v34
	v_mul_f32_e32 v104, v88, v104
	v_mul_f32_e32 v96, v88, v96
	v_mul_f32_e32 v92, v88, v92
	v_mul_f32_e32 v80, v88, v80
	v_mul_f32_e32 v72, v88, v72
	s_waitcnt vmcnt(0)
; __device__ __forceinline__ unsigned cvt_pk_bf16(float lo, float hi) { unsigned r; asm volatile("v_cvt_pk_bf16_f32 %0, %1, %2" : "=v"(r) : "v"(lo), "v"(hi)); return r; }
; __device__ __forceinline__ float bflo(unsigned w) { return __uint_as_float(w << 16); }
; __device__ __forceinline__ float bfhi(unsigned w) { return __uint_as_float(w & 0xffff0000u); }
; template <int MODE>
; __device__ void row_pass(const Params& p, const bf16_t* d, int ldd, const float* g0, const float* g1, bf16_t* xs, bf16_t* xn, float* out) {
;     ...
;       const float rs = rsqrtf(ss * (1.0f / DM) + 1e-6f) * (MODE == 2 ? 1.0f : 0.5f);
; #pragma unroll
;       for (int i = 0; i < 8; ++i) {
;         const f32x4 gg = *(const f32x4*)(g0 + i * 256 + lane * 4);
;         float r[4];
; #pragma unroll
;         for (int j = 0; j < 4; ++j) r[j] = xv[i * 4 + j] + dv[i * 4 + j] * rs * gg[j];
;         if (MODE == 3) {
;           *(f32x4*)(out + (size_t)row * DM + i * 256 + lane * 4) = (f32x4){r[0], r[1], r[2], r[3]};
;         } else {
;           const unsigned w0 = cvt_pk_bf16(r[0], r[1]), w1 = cvt_pk_bf16(r[2], r[3]);
;           *(u32x2*)(xs + (size_t)row * DM + i * 256 + lane * 4) = (u32x2){w0, w1};
;           xv[i * 4] = bflo(w0); xv[i * 4 + 1] = bfhi(w0); xv[i * 4 + 2] = bflo(w1); xv[i * 4 + 3] = bfhi(w1);
;         }
;       }
;     }
;     if (MODE != 3) {
;       float ss = 0.f;
; #pragma unroll
;       for (int i = 0; i < 32; ++i) ss += xv[i] * xv[i];
	v_fma_f32 v28, v132, v104, v28
	v_mul_f32_e32 v34, v88, v103
	v_fma_f32 v29, v133, v34, v29
	v_mul_f32_e32 v34, v88, v101
	v_fma_f32 v30, v134, v34, v30
	v_mul_f32_e32 v34, v88, v99
	v_fmac_f32_e32 v31, v135, v34
	v_cvt_pk_bf16_f32 v34, v28, v29
	v_cvt_pk_bf16_f32 v35, v30, v31
	global_store_dwordx2 v[60:61], v[34:35], off
	v_lshlrev_b32_e32 v31, 16, v34
	v_and_b32_e32 v30, 0xffff0000, v34
	v_lshlrev_b32_e32 v29, 16, v35
	v_and_b32_e32 v28, 0xffff0000, v35
	v_mul_f32_e32 v99, v88, v102
	v_fma_f32 v24, v136, v99, v24
	v_mul_f32_e32 v34, v88, v100
	v_fma_f32 v25, v137, v34, v25
	v_mul_f32_e32 v34, v88, v98
	v_fma_f32 v26, v138, v34, v26
	v_mul_f32_e32 v34, v88, v97
	v_fmac_f32_e32 v27, v139, v34
	v_cvt_pk_bf16_f32 v34, v24, v25
	v_cvt_pk_bf16_f32 v35, v26, v27
	global_store_dwordx2 v[60:61], v[34:35], off offset:512
	v_lshlrev_b32_e32 v27, 16, v34
	v_and_b32_e32 v26, 0xffff0000, v34
	v_lshlrev_b32_e32 v25, 16, v35
	v_and_b32_e32 v24, 0xffff0000, v35
	v_fma_f32 v20, v140, v96, v20
	v_mul_f32_e32 v34, v88, v95
	v_fma_f32 v21, v141, v34, v21
	v_mul_f32_e32 v34, v88, v94
	v_fma_f32 v22, v142, v34, v22
	v_mul_f32_e32 v34, v88, v93
	v_fmac_f32_e32 v23, v143, v34
	v_cvt_pk_bf16_f32 v34, v20, v21
	v_cvt_pk_bf16_f32 v35, v22, v23
	global_store_dwordx2 v[60:61], v[34:35], off offset:1024
	v_lshlrev_b32_e32 v23, 16, v34
	v_and_b32_e32 v22, 0xffff0000, v34
	v_lshlrev_b32_e32 v21, 16, v35
	v_and_b32_e32 v20, 0xffff0000, v35
	v_fma_f32 v16, v144, v92, v16
	v_mul_f32_e32 v34, v88, v91
	v_fma_f32 v17, v145, v34, v17
	v_mul_f32_e32 v34, v88, v90
	v_fma_f32 v18, v146, v34, v18
	v_mul_f32_e32 v34, v88, v89
	v_fmac_f32_e32 v19, v147, v34
	v_cvt_pk_bf16_f32 v34, v16, v17
	v_cvt_pk_bf16_f32 v35, v18, v19
	global_store_dwordx2 v[60:61], v[34:35], off offset:1536
	v_lshlrev_b32_e32 v19, 16, v34
	v_and_b32_e32 v18, 0xffff0000, v34
	v_lshlrev_b32_e32 v17, 16, v35
	v_and_b32_e32 v16, 0xffff0000, v35
	v_fma_f32 v12, v80, v148, v12
	v_mul_f32_e32 v34, v88, v78
	v_fma_f32 v13, v34, v149, v13
	v_mul_f32_e32 v34, v88, v76
	v_fma_f32 v14, v34, v150, v14
	v_mul_f32_e32 v34, v88, v74
	v_fmac_f32_e32 v15, v34, v151
	v_cvt_pk_bf16_f32 v34, v12, v13
	v_cvt_pk_bf16_f32 v35, v14, v15
	global_store_dwordx2 v[60:61], v[34:35], off offset:2048
	v_lshlrev_b32_e32 v15, 16, v34
	v_and_b32_e32 v14, 0xffff0000, v34
	v_lshlrev_b32_e32 v13, 16, v35
	v_and_b32_e32 v12, 0xffff0000, v35
	v_mul_f32_e32 v74, v88, v81
	v_fma_f32 v8, v74, v152, v8
	v_mul_f32_e32 v34, v88, v79
	v_fma_f32 v9, v34, v153, v9
	v_mul_f32_e32 v34, v88, v77
	v_fma_f32 v10, v34, v154, v10
	v_mul_f32_e32 v34, v88, v75
	v_fmac_f32_e32 v11, v34, v155
	v_cvt_pk_bf16_f32 v34, v8, v9
	v_cvt_pk_bf16_f32 v35, v10, v11
	global_store_dwordx2 v[60:61], v[34:35], off offset:2560
	v_lshlrev_b32_e32 v11, 16, v34
	v_and_b32_e32 v10, 0xffff0000, v34
	v_lshlrev_b32_e32 v9, 16, v35
	v_and_b32_e32 v8, 0xffff0000, v35
	v_fma_f32 v4, v72, v156, v4
	v_mul_f32_e32 v34, v88, v70
	v_fma_f32 v5, v34, v157, v5
	v_mul_f32_e32 v34, v88, v68
	v_fma_f32 v6, v34, v158, v6
	v_mul_f32_e32 v34, v88, v66
	v_fmac_f32_e32 v7, v34, v159
	v_cvt_pk_bf16_f32 v34, v4, v5
	v_cvt_pk_bf16_f32 v35, v6, v7
	global_store_dwordx2 v[60:61], v[34:35], off offset:3072
	v_lshlrev_b32_e32 v7, 16, v34
	v_and_b32_e32 v6, 0xffff0000, v34
	v_lshlrev_b32_e32 v5, 16, v35
	v_and_b32_e32 v4, 0xffff0000, v35
	v_mul_f32_e32 v66, v88, v73
	v_fma_f32 v0, v66, v160, v0
	v_mul_f32_e32 v34, v88, v71
	v_fma_f32 v1, v34, v161, v1
	v_mul_f32_e32 v34, v88, v69
	v_fma_f32 v34, v34, v162, v2
	v_mul_f32_e32 v2, v88, v67
	v_fmac_f32_e32 v3, v2, v163
	v_cvt_pk_bf16_f32 v2, v0, v1
	v_cvt_pk_bf16_f32 v3, v34, v3
	global_store_dwordx2 v[60:61], v[2:3], off offset:3584
	v_mul_f32_e32 v36, v30, v30
	v_fmac_f32_e32 v36, v31, v31
	v_fmac_f32_e32 v36, v29, v29
	v_fmac_f32_e32 v36, v28, v28
	v_fmac_f32_e32 v36, v27, v27
	v_fmac_f32_e32 v36, v26, v26
	v_fmac_f32_e32 v36, v25, v25
	v_fmac_f32_e32 v36, v24, v24
	v_fmac_f32_e32 v36, v23, v23
	v_fmac_f32_e32 v36, v22, v22
	v_fmac_f32_e32 v36, v21, v21
	v_fmac_f32_e32 v36, v20, v20
	v_fmac_f32_e32 v36, v19, v19
	v_fmac_f32_e32 v36, v18, v18
	v_fmac_f32_e32 v36, v17, v17
	v_fmac_f32_e32 v36, v16, v16
	v_fmac_f32_e32 v36, v15, v15
	v_fmac_f32_e32 v36, v14, v14
	v_fmac_f32_e32 v36, v13, v13
	v_fmac_f32_e32 v36, v12, v12
	v_fmac_f32_e32 v36, v11, v11
	v_fmac_f32_e32 v36, v10, v10
	v_fmac_f32_e32 v36, v9, v9
	v_fmac_f32_e32 v36, v8, v8
	v_fmac_f32_e32 v36, v7, v7
	v_fmac_f32_e32 v36, v6, v6
	v_fmac_f32_e32 v36, v5, v5
	v_and_b32_e32 v0, 0xffff0000, v2
	v_lshlrev_b32_e32 v1, 16, v2
	v_fmac_f32_e32 v36, v4, v4
	v_pk_mul_f32 v[34:35], v[0:1], v[0:1]
	v_lshl_add_u64 v[60:61], v[60:61], 0, s[28:29]
	v_add_f32_e32 v2, v36, v35
	v_add_f32_e32 v36, v34, v2
	v_and_b32_e32 v2, 0xffff0000, v3
	v_lshlrev_b32_e32 v3, 16, v3
	v_pk_mul_f32 v[34:35], v[2:3], v[2:3]
	s_nop 0
	v_add_f32_e32 v35, v35, v36
	v_add_f32_e32 v34, v34, v35
	ds_bpermute_b32 v35, v82, v34
	s_waitcnt lgkmcnt(0)
; __device__ __forceinline__ unsigned cvt_pk_bf16(float lo, float hi) { unsigned r; asm volatile("v_cvt_pk_bf16_f32 %0, %1, %2" : "=v"(r) : "v"(lo), "v"(hi)); return r; }
; template <int MODE>
; __device__ void row_pass(const Params& p, const bf16_t* d, int ldd, const float* g0, const float* g1, bf16_t* xs, bf16_t* xn, float* out) {
;     ...
;       ss = wave_sum(ss);
;       const float rs = rsqrtf(ss * (1.0f / DM) + 1e-6f);
;       const float* gn = (MODE == 0) ? g0 : g1;
; #pragma unroll
;       for (int i = 0; i < 8; ++i) {
;         const f32x4 gg = *(const f32x4*)(gn + i * 256 + lane * 4);
;         const unsigned w0 = cvt_pk_bf16(xv[i * 4] * rs * gg[0], xv[i * 4 + 1] * rs * gg[1]), w1 = cvt_pk_bf16(xv[i * 4 + 2] * rs * gg[2], xv[i * 4 + 3] * rs * gg[3]);
;         *(u32x2*)(xn + (size_t)row * DM + i * 256 + lane * 4) = (u32x2){w0, w1};
;       }
	v_add_f32_e32 v34, v34, v35
	ds_bpermute_b32 v35, v83, v34
	s_waitcnt lgkmcnt(0)
	v_add_f32_e32 v34, v34, v35
	ds_bpermute_b32 v35, v84, v34
	s_waitcnt lgkmcnt(0)
	v_add_f32_e32 v34, v34, v35
	ds_bpermute_b32 v35, v85, v34
	s_waitcnt lgkmcnt(0)
	v_add_f32_e32 v34, v34, v35
	ds_bpermute_b32 v35, v86, v34
	s_waitcnt lgkmcnt(0)
	v_add_f32_e32 v34, v34, v35
	ds_bpermute_b32 v35, v87, v34
	s_waitcnt lgkmcnt(0)
	v_add_f32_e32 v34, v34, v35
	v_fmamk_f32 v34, v34, 0x3a000000, v131
	v_cmp_gt_f32_e32 vcc, s61, v34
	v_mul_f32_e32 v35, 0x4b800000, v34
	s_nop 0
	v_cndmask_b32_e32 v34, v34, v35, vcc
	v_rsq_f32_e32 v34, v34
	s_nop 0
	v_mul_f32_e32 v35, 0x45800000, v34
	v_cndmask_b32_e32 v34, v34, v35, vcc
	v_mul_f32_e32 v31, v34, v31
	v_mul_f32_e32 v30, v34, v30
	v_mul_f32_e32 v31, v164, v31
	v_mul_f32_e32 v30, v165, v30
	v_mul_f32_e32 v29, v34, v29
	v_mul_f32_e32 v28, v34, v28
	v_cvt_pk_bf16_f32 v30, v31, v30
	v_mul_f32_e32 v29, v166, v29
	v_mul_f32_e32 v28, v167, v28
	v_cvt_pk_bf16_f32 v31, v29, v28
	global_store_dwordx2 v[64:65], v[30:31], off
	v_mul_f32_e32 v27, v34, v27
	v_mul_f32_e32 v26, v34, v26
	v_mul_f32_e32 v25, v34, v25
	v_mul_f32_e32 v24, v34, v24
	v_mul_f32_e32 v23, v34, v23
	v_mul_f32_e32 v22, v34, v22
	v_mul_f32_e32 v21, v34, v21
	v_mul_f32_e32 v20, v34, v20
	v_mul_f32_e32 v19, v34, v19
	v_mul_f32_e32 v18, v34, v18
	v_mul_f32_e32 v17, v34, v17
	v_mul_f32_e32 v16, v34, v16
	v_mul_f32_e32 v15, v34, v15
	v_mul_f32_e32 v14, v34, v14
	v_mul_f32_e32 v13, v34, v13
	v_mul_f32_e32 v12, v34, v12
	v_mul_f32_e32 v11, v34, v11
	v_mul_f32_e32 v10, v34, v10
	v_mul_f32_e32 v9, v34, v9
	v_mul_f32_e32 v8, v34, v8
	v_mul_f32_e32 v7, v34, v7
	v_mul_f32_e32 v6, v34, v6
	v_mul_f32_e32 v5, v34, v5
	v_mul_f32_e32 v4, v34, v4
	v_mul_f32_e32 v1, v34, v1
	v_mul_f32_e32 v0, v34, v0
	v_cmp_lt_i32_e32 vcc, s62, v38
	v_mul_f32_e32 v2, v34, v2
	s_or_b64 s[14:15], vcc, s[14:15]
	v_mul_f32_e32 v27, v168, v27
	v_mul_f32_e32 v26, v169, v26
	v_cvt_pk_bf16_f32 v26, v27, v26
	v_mul_f32_e32 v25, v170, v25
	v_mul_f32_e32 v24, v171, v24
	v_cvt_pk_bf16_f32 v27, v25, v24
	global_store_dwordx2 v[62:63], v[26:27], off offset:-3584
	v_mul_f32_e32 v23, v172, v23
	v_mul_f32_e32 v22, v173, v22
	v_cvt_pk_bf16_f32 v22, v23, v22
	v_mul_f32_e32 v21, v174, v21
	v_mul_f32_e32 v20, v175, v20
	v_cvt_pk_bf16_f32 v23, v21, v20
	global_store_dwordx2 v[62:63], v[22:23], off offset:-3072
	v_mul_f32_e32 v19, v19, v176
	v_mul_f32_e32 v18, v18, v177
	v_cvt_pk_bf16_f32 v18, v19, v18
	v_mul_f32_e32 v17, v17, v178
	v_mul_f32_e32 v16, v16, v179
	v_cvt_pk_bf16_f32 v19, v17, v16
	global_store_dwordx2 v[62:63], v[18:19], off offset:-2560
	v_mul_f32_e32 v15, v15, v180
	v_mul_f32_e32 v14, v14, v181
	v_cvt_pk_bf16_f32 v14, v15, v14
	v_mul_f32_e32 v13, v13, v182
	v_mul_f32_e32 v12, v12, v183
	v_cvt_pk_bf16_f32 v15, v13, v12
	global_store_dwordx2 v[62:63], v[14:15], off offset:-2048
	v_mul_f32_e32 v11, v11, v184
	v_mul_f32_e32 v10, v10, v185
	v_cvt_pk_bf16_f32 v10, v11, v10
	v_mul_f32_e32 v9, v9, v186
	v_mul_f32_e32 v8, v8, v187
	v_cvt_pk_bf16_f32 v11, v9, v8
	global_store_dwordx2 v[62:63], v[10:11], off offset:-1536
	v_mul_f32_e32 v7, v7, v188
	v_mul_f32_e32 v6, v6, v189
	v_cvt_pk_bf16_f32 v6, v7, v6
	v_mul_f32_e32 v5, v5, v190
	v_mul_f32_e32 v4, v4, v191
	v_cvt_pk_bf16_f32 v7, v5, v4
	global_store_dwordx2 v[62:63], v[6:7], off offset:-1024
	v_mul_f32_e32 v1, v1, v192
	v_mul_f32_e32 v0, v0, v193
	v_cvt_pk_bf16_f32 v0, v1, v0
	v_mul_f32_e32 v1, v34, v3
	v_mul_f32_e32 v1, v1, v194
	v_mul_f32_e32 v2, v2, v195
	v_cvt_pk_bf16_f32 v1, v1, v2
	global_store_dwordx2 v[62:63], v[0:1], off offset:-512
	s_andn2_b64 exec, exec, s[14:15]
	s_cbranch_execnz .LBB0_1250
